# row phases: non-temporal hint on all streamed-once row loads (residual stream and GEMM outputs read once)
# speedup vs baseline: 1.0047x; 1.0030x over previous
.LBB0_764:
	v_lshl_add_u64 v[74:75], s[8:9], 0, v[32:33]
	v_lshl_add_u64 v[72:73], s[10:11], 0, v[32:33]
	v_add_co_u32_e64 v104, s[4:5], s23, v74
	v_lshl_add_u64 v[16:17], s[18:19], 0, v[66:67]
	v_lshl_add_u64 v[76:77], s[14:15], 0, v[66:67]
	v_add_co_u32_e32 v102, vcc, 0x4000000, v72
	v_addc_co_u32_e64 v105, s[4:5], 0, v75, s[4:5]
	global_load_dwordx4 v[86:89], v[16:17], off nt
	global_load_dwordx4 v[90:93], v[16:17], off offset:1024 nt
	global_load_dwordx4 v[94:97], v[16:17], off offset:2048 nt
	global_load_dwordx4 v[98:101], v[16:17], off offset:3072 nt
	global_load_dwordx4 v[28:31], v[76:77], off nt
	global_load_dwordx4 v[24:27], v[76:77], off offset:1024 nt
	global_load_dwordx4 v[20:23], v[76:77], off offset:2048 nt
	s_nop 0
	global_load_dwordx4 v[16:19], v[76:77], off offset:3072 nt
	v_add_co_u32_e64 v76, s[4:5], s25, v72
	v_addc_co_u32_e32 v103, vcc, 0, v73, vcc
	s_nop 0
	v_addc_co_u32_e64 v77, s[4:5], 0, v73, s[4:5]
	global_load_dwordx2 v[106:107], v[104:105], off offset:1536 nt
	global_load_dwordx2 v[108:109], v[104:105], off nt
	global_load_dwordx2 v[110:111], v[104:105], off offset:512 nt
	global_load_dwordx2 v[112:113], v[104:105], off offset:1024 nt
	global_load_dwordx2 v[72:73], v[102:103], off offset:1536 nt
	s_nop 0
	global_load_dwordx2 v[104:105], v[102:103], off nt
	global_load_dwordx2 v[114:115], v[102:103], off offset:512 nt
	global_load_dwordx2 v[116:117], v[102:103], off offset:1024 nt
	v_lshl_add_u64 v[70:71], s[16:17], 0, v[32:33]
	v_add_co_u32_e64 v74, s[4:5], s25, v74
	v_lshl_add_u64 v[78:79], s[12:13], 0, v[32:33]
	s_nop 0
	v_addc_co_u32_e64 v75, s[4:5], 0, v75, s[4:5]
	s_add_i32 s22, s22, 2
	s_add_u32 s8, s8, 0x1000
	s_addc_u32 s9, s9, 0
	s_add_u32 s10, s10, 0x1000
	s_addc_u32 s11, s11, 0
	s_add_u32 s12, s12, 0x1000
	s_addc_u32 s13, s13, 0
	s_add_u32 s14, s14, 0x2000
	s_addc_u32 s15, s15, 0
	s_add_u32 s16, s16, 0x1000
	s_addc_u32 s17, s17, 0
	s_add_u32 s18, s18, 0x2000
	s_addc_u32 s19, s19, 0
	s_cmp_lt_i32 s22, s21
	s_waitcnt vmcnt(7)
	v_lshlrev_b32_e32 v103, 16, v106
	s_waitcnt vmcnt(6)
	v_lshlrev_b32_e32 v120, 16, v108
	v_and_b32_e32 v121, 0xffff0000, v108
	v_lshlrev_b32_e32 v108, 16, v109
	v_and_b32_e32 v109, 0xffff0000, v109
	s_waitcnt vmcnt(5)
	v_lshlrev_b32_e32 v123, 16, v111
	v_lshlrev_b32_e32 v122, 16, v110
	v_and_b32_e32 v111, 0xffff0000, v111
	v_and_b32_e32 v110, 0xffff0000, v110
	s_waitcnt vmcnt(2)
	v_lshlrev_b32_e32 v130, 16, v104
	v_and_b32_e32 v131, 0xffff0000, v104
	v_lshlrev_b32_e32 v104, 16, v105
	v_and_b32_e32 v105, 0xffff0000, v105
	s_waitcnt vmcnt(1)
	v_lshlrev_b32_e32 v133, 16, v115
	v_lshlrev_b32_e32 v132, 16, v114
	v_and_b32_e32 v115, 0xffff0000, v115
	v_and_b32_e32 v114, 0xffff0000, v114
	v_lshlrev_b32_e32 v124, 16, v112
	v_and_b32_e32 v125, 0xffff0000, v112
	v_lshlrev_b32_e32 v112, 16, v113
	v_and_b32_e32 v113, 0xffff0000, v113
	v_lshlrev_b32_e32 v127, 16, v72
	v_mul_f32_e32 v102, v109, v109
	v_pk_mul_f32 v[136:137], v[110:111], v[110:111]
	v_mul_f32_e32 v126, v121, v121
	v_mul_f32_e32 v144, v105, v105
	v_pk_mul_f32 v[146:147], v[114:115], v[114:115]
	v_mul_f32_e32 v148, v131, v131
	v_and_b32_e32 v119, 0xffff0000, v106
	v_lshlrev_b32_e32 v106, 16, v107
	s_waitcnt vmcnt(0)
	v_lshlrev_b32_e32 v134, 16, v116
	v_and_b32_e32 v135, 0xffff0000, v116
	v_lshlrev_b32_e32 v116, 16, v117
	v_and_b32_e32 v117, 0xffff0000, v117
	v_mov_b32_e32 v139, v103
	v_mul_f32_e32 v138, v125, v125
	v_mul_f32_e32 v140, v113, v113
	v_mov_b32_e32 v142, v122
	v_mov_b32_e32 v143, v110
	v_mov_b32_e32 v110, v123
	v_mov_b32_e32 v141, v127
	v_mov_b32_e32 v154, v132
	v_mov_b32_e32 v155, v114
	v_mov_b32_e32 v114, v133
	v_pk_fma_f32 v[156:157], v[108:109], v[108:109], v[102:103] op_sel_hi:[1,1,0]
	v_pk_fma_f32 v[122:123], v[122:123], v[122:123], v[136:137]
	v_pk_fma_f32 v[136:137], v[120:121], v[120:121], v[126:127] op_sel_hi:[1,1,0]
	v_pk_fma_f32 v[144:145], v[104:105], v[104:105], v[144:145] op_sel_hi:[1,1,0]
	v_pk_fma_f32 v[132:133], v[132:133], v[132:133], v[146:147]
	v_pk_fma_f32 v[146:147], v[130:131], v[130:131], v[148:149] op_sel_hi:[1,1,0]
	v_and_b32_e32 v129, 0xffff0000, v72
	v_lshlrev_b32_e32 v72, 16, v73
	v_and_b32_e32 v73, 0xffff0000, v73
	v_mul_f32_e32 v153, v106, v106
	v_mul_f32_e32 v150, v135, v135
	v_mul_f32_e32 v152, v117, v117
	v_pk_fma_f32 v[158:159], v[124:125], v[124:125], v[138:139] op_sel_hi:[1,1,0]
	v_pk_fma_f32 v[160:161], v[112:113], v[112:113], v[140:141] op_sel_hi:[1,1,0]
	v_mov_b32_e32 v102, v136
	v_mov_b32_e32 v138, v156
	v_mov_b32_e32 v126, v146
	v_mov_b32_e32 v140, v144
	v_and_b32_e32 v107, 0xffff0000, v107
	v_mul_f32_e32 v85, v119, v119
	v_mov_b32_e32 v118, v103
	v_mul_f32_e32 v163, v129, v129
	v_mul_f32_e32 v164, v72, v72
	v_mul_f32_e32 v165, v73, v73
	v_mov_b32_e32 v128, v127
	v_pk_fma_f32 v[148:149], v[134:135], v[134:135], v[150:151] op_sel_hi:[1,1,0]
	v_pk_fma_f32 v[150:151], v[116:117], v[116:117], v[152:153] op_sel_hi:[1,1,0]
	v_pk_add_f32 v[136:137], v[136:137], v[156:157]
	v_pk_add_f32 v[122:123], v[122:123], v[122:123] op_sel:[0,1] op_sel_hi:[1,0]
	v_pk_add_f32 v[144:145], v[146:147], v[144:145]
	v_pk_add_f32 v[132:133], v[132:133], v[132:133] op_sel:[0,1] op_sel_hi:[1,0]
	v_pk_mul_f32 v[102:103], v[102:103], v[138:139]
	v_pk_mul_f32 v[126:127], v[126:127], v[140:141]
	v_mul_f32_e32 v162, v107, v107
	v_mov_b32_e32 v149, v164
	v_mov_b32_e32 v151, v165
	v_mov_b32_e32 v123, v85
	v_mov_b32_e32 v133, v163
	v_mov_b32_e32 v137, v103
	v_mov_b32_e32 v145, v127
	v_mov_b32_e32 v159, v153
	v_mov_b32_e32 v161, v162
	v_pk_add_f32 v[140:141], v[148:149], v[150:151]
	v_pk_add_f32 v[102:103], v[136:137], v[122:123]
	v_pk_add_f32 v[122:123], v[144:145], v[132:133]
	v_pk_add_f32 v[138:139], v[158:159], v[160:161]
	v_pk_add_f32 v[122:123], v[122:123], v[140:141]
	v_pk_add_f32 v[102:103], v[102:103], v[138:139]
	v_add_f32_e32 v85, v122, v123
	v_mov_b32_e32 v126, v102
	ds_bpermute_b32 v102, v69, v85
	s_waitcnt lgkmcnt(0)
	v_add_f32_e32 v85, v85, v102
	ds_bpermute_b32 v102, v80, v85
	s_waitcnt lgkmcnt(0)
	v_add_f32_e32 v85, v85, v102
	ds_bpermute_b32 v102, v81, v85
	s_waitcnt lgkmcnt(0)
	v_add_f32_e32 v85, v85, v102
	ds_bpermute_b32 v102, v82, v85
	s_waitcnt lgkmcnt(0)
	v_add_f32_e32 v85, v85, v102
	ds_bpermute_b32 v102, v83, v85
	s_waitcnt lgkmcnt(0)
	v_add_f32_e32 v85, v85, v102
	ds_bpermute_b32 v102, v84, v85
	s_waitcnt lgkmcnt(0)
	v_add_f32_e32 v85, v85, v102
	v_fmamk_f32 v85, v85, 0x3a800000, v68
	v_mul_f32_e32 v102, 0x4b800000, v85
	v_cmp_gt_f32_e32 vcc, s24, v85
	s_nop 1
	v_cndmask_b32_e32 v85, v85, v102, vcc
	v_rsq_f32_e32 v85, v85
	s_nop 0
	v_mul_f32_e32 v102, 0x45800000, v85
	v_cndmask_b32_e32 v102, v85, v102, vcc
	v_pk_mul_f32 v[122:123], v[102:103], v[130:131] op_sel_hi:[0,1]
	v_pk_mul_f32 v[104:105], v[102:103], v[104:105] op_sel_hi:[0,1]
	v_pk_mul_f32 v[130:131], v[102:103], v[154:155] op_sel_hi:[0,1]
	v_pk_mul_f32 v[114:115], v[102:103], v[114:115] op_sel_hi:[0,1]
	v_pk_mul_f32 v[132:133], v[102:103], v[134:135] op_sel_hi:[0,1]
	v_pk_mul_f32 v[116:117], v[102:103], v[116:117] op_sel_hi:[0,1]
	v_pk_mul_f32 v[128:129], v[102:103], v[128:129] op_sel_hi:[0,1]
	v_pk_mul_f32 v[72:73], v[102:103], v[72:73] op_sel_hi:[0,1]
	v_pk_fma_f32 v[88:89], v[34:35], v[104:105], v[88:89]
	v_pk_fma_f32 v[86:87], v[36:37], v[122:123], v[86:87]
	v_pk_fma_f32 v[92:93], v[38:39], v[114:115], v[92:93]
	v_pk_fma_f32 v[90:91], v[40:41], v[130:131], v[90:91]
	v_pk_fma_f32 v[96:97], v[42:43], v[116:117], v[96:97]
	v_pk_fma_f32 v[94:95], v[44:45], v[132:133], v[94:95]
	v_pk_fma_f32 v[72:73], v[46:47], v[72:73], v[100:101]
	v_pk_fma_f32 v[98:99], v[48:49], v[128:129], v[98:99]
	v_cvt_pk_bf16_f32 v86, v86, v87
	v_cvt_pk_bf16_f32 v87, v88, v89
	v_cvt_pk_bf16_f32 v88, v90, v91
	v_cvt_pk_bf16_f32 v89, v92, v93
	v_cvt_pk_bf16_f32 v90, v94, v95
	v_cvt_pk_bf16_f32 v91, v96, v97
	v_cvt_pk_bf16_f32 v92, v98, v99
	v_cvt_pk_bf16_f32 v93, v72, v73
	global_store_dwordx2 v[70:71], v[86:87], off
	global_store_dwordx2 v[70:71], v[88:89], off offset:512
	global_store_dwordx2 v[70:71], v[90:91], off offset:1024
	v_lshlrev_b32_e32 v95, 16, v87
	v_lshlrev_b32_e32 v94, 16, v86
	v_and_b32_e32 v87, 0xffff0000, v87
	v_and_b32_e32 v86, 0xffff0000, v86
	v_lshlrev_b32_e32 v97, 16, v89
	v_lshlrev_b32_e32 v96, 16, v88
	v_and_b32_e32 v89, 0xffff0000, v89
	v_and_b32_e32 v88, 0xffff0000, v88
	v_lshlrev_b32_e32 v72, 16, v90
	v_and_b32_e32 v73, 0xffff0000, v90
	global_store_dwordx2 v[70:71], v[92:93], off offset:1536
	v_lshlrev_b32_e32 v70, 16, v92
	v_lshlrev_b32_e32 v90, 16, v91
	v_pk_mul_f32 v[98:99], v[86:87], v[86:87]
	v_pk_mul_f32 v[100:101], v[88:89], v[88:89]
	v_and_b32_e32 v91, 0xffff0000, v91
	v_mul_f32_e32 v71, v72, v72
	v_mul_f32_e32 v105, v73, v73
	v_mul_f32_e32 v102, v90, v90
	v_mov_b32_e32 v104, v70
	v_mov_b32_e32 v116, v94
	v_mov_b32_e32 v117, v86
	v_mov_b32_e32 v86, v95
	v_mov_b32_e32 v122, v96
	v_mov_b32_e32 v123, v88
	v_mov_b32_e32 v88, v97
	v_pk_fma_f32 v[94:95], v[94:95], v[94:95], v[98:99]
	v_pk_fma_f32 v[96:97], v[96:97], v[96:97], v[100:101]
	v_and_b32_e32 v85, 0xffff0000, v92
	v_lshlrev_b32_e32 v92, 16, v93
	v_and_b32_e32 v93, 0xffff0000, v93
	v_pk_fma_f32 v[98:99], v[90:91], v[90:91], v[102:103] op_sel_hi:[1,1,0]
	v_pk_add_f32 v[100:101], v[70:71], v[104:105]
	v_pk_add_f32 v[94:95], v[94:95], v[94:95] op_sel_hi:[0,1]
	v_pk_add_f32 v[96:97], v[96:97], v[96:97] op_sel_hi:[0,1]
	v_mul_f32_e32 v114, v70, v70
	v_mul_f32_e32 v98, v85, v85
	v_mov_b32_e32 v115, v101
	v_mul_f32_e32 v94, v92, v92
	v_mul_f32_e32 v96, v93, v93
	v_pk_add_f32 v[98:99], v[114:115], v[98:99]
	v_pk_add_f32 v[94:95], v[94:95], v[96:97]
	v_mov_b32_e32 v71, v85
	v_pk_add_f32 v[94:95], v[98:99], v[94:95]
	s_nop 0
	v_mov_b32_e32 v127, v94
	v_mov_b32_e32 v94, v103
	v_pk_add_f32 v[94:95], v[126:127], v[94:95]
	ds_bpermute_b32 v97, v69, v95
	ds_bpermute_b32 v96, v69, v94
	s_waitcnt lgkmcnt(0)
	v_pk_add_f32 v[94:95], v[94:95], v[96:97]
	ds_bpermute_b32 v97, v80, v95
	ds_bpermute_b32 v96, v80, v94
	s_waitcnt lgkmcnt(0)
	v_pk_add_f32 v[94:95], v[94:95], v[96:97]
	ds_bpermute_b32 v97, v81, v95
	ds_bpermute_b32 v96, v81, v94
	s_waitcnt lgkmcnt(0)
	v_pk_add_f32 v[94:95], v[94:95], v[96:97]
	ds_bpermute_b32 v97, v82, v95
	ds_bpermute_b32 v96, v82, v94
	s_waitcnt lgkmcnt(0)
	v_pk_add_f32 v[94:95], v[94:95], v[96:97]
	ds_bpermute_b32 v97, v83, v95
	ds_bpermute_b32 v96, v83, v94
	s_waitcnt lgkmcnt(0)
	v_pk_add_f32 v[94:95], v[94:95], v[96:97]
	ds_bpermute_b32 v97, v84, v95
	ds_bpermute_b32 v96, v84, v94
	s_waitcnt lgkmcnt(0)
	v_pk_add_f32 v[94:95], v[94:95], v[96:97]
	s_nop 0
	v_pk_fma_f32 v[94:95], v[94:95], s[20:21], v[68:69] op_sel_hi:[1,0,0]
	s_nop 0
	v_mul_f32_e32 v85, 0x4b800000, v95
	v_mul_f32_e32 v96, 0x4b800000, v94
	v_cmp_gt_f32_e32 vcc, s24, v94
	v_cmp_gt_f32_e64 s[4:5], s24, v95
	s_nop 0
	v_cndmask_b32_e32 v94, v94, v96, vcc
	v_cndmask_b32_e64 v85, v95, v85, s[4:5]
	v_rsq_f32_e32 v85, v85
	v_rsq_f32_e32 v95, v94
	v_mul_f32_e32 v94, 0x45800000, v85
	v_mul_f32_e32 v96, 0x45800000, v95
	v_cndmask_b32_e64 v94, v85, v94, s[4:5]
	v_cndmask_b32_e32 v96, v95, v96, vcc
	v_pk_mul_f32 v[98:99], v[94:95], v[116:117] op_sel_hi:[0,1]
	v_pk_mul_f32 v[86:87], v[94:95], v[86:87] op_sel_hi:[0,1]
	v_pk_mul_f32 v[100:101], v[94:95], v[122:123] op_sel_hi:[0,1]
	v_pk_mul_f32 v[88:89], v[94:95], v[88:89] op_sel_hi:[0,1]
	v_pk_mul_f32 v[72:73], v[94:95], v[72:73] op_sel_hi:[0,1]
	v_pk_mul_f32 v[90:91], v[94:95], v[90:91] op_sel_hi:[0,1]
	v_pk_mul_f32 v[70:71], v[94:95], v[70:71] op_sel_hi:[0,1]
	v_pk_mul_f32 v[92:93], v[94:95], v[92:93] op_sel_hi:[0,1]
	v_pk_mul_f32 v[94:95], v[96:97], v[120:121] op_sel_hi:[0,1]
	v_pk_mul_f32 v[102:103], v[96:97], v[108:109] op_sel_hi:[0,1]
	v_pk_mul_f32 v[104:105], v[96:97], v[142:143] op_sel_hi:[0,1]
	v_pk_mul_f32 v[108:109], v[96:97], v[110:111] op_sel_hi:[0,1]
	v_pk_mul_f32 v[110:111], v[96:97], v[124:125] op_sel_hi:[0,1]
	v_pk_mul_f32 v[112:113], v[96:97], v[112:113] op_sel_hi:[0,1]
	v_pk_mul_f32 v[114:115], v[96:97], v[118:119] op_sel_hi:[0,1]
	v_pk_fma_f32 v[86:87], v[50:51], v[86:87], v[2:3]
	v_pk_fma_f32 v[98:99], v[52:53], v[98:99], v[0:1]
	v_pk_fma_f32 v[30:31], v[34:35], v[102:103], v[30:31]
	v_pk_fma_f32 v[28:29], v[36:37], v[94:95], v[28:29]
	v_pk_fma_f32 v[26:27], v[38:39], v[108:109], v[26:27]
	v_pk_fma_f32 v[24:25], v[40:41], v[104:105], v[24:25]
	v_pk_mul_f32 v[96:97], v[96:97], v[106:107] op_sel_hi:[0,1]
	v_pk_fma_f32 v[88:89], v[54:55], v[88:89], v[6:7]
	v_pk_fma_f32 v[100:101], v[56:57], v[100:101], v[4:5]
	v_pk_fma_f32 v[90:91], v[58:59], v[90:91], v[10:11]
	v_pk_fma_f32 v[72:73], v[60:61], v[72:73], v[8:9]
	v_pk_fma_f32 v[92:93], v[62:63], v[92:93], v[14:15]
	v_pk_fma_f32 v[70:71], v[64:65], v[70:71], v[12:13]
	v_pk_fma_f32 v[22:23], v[42:43], v[112:113], v[22:23]
	v_pk_fma_f32 v[20:21], v[44:45], v[110:111], v[20:21]
	v_pk_fma_f32 v[16:17], v[48:49], v[114:115], v[16:17]
	v_cvt_pk_bf16_f32 v94, v98, v99
	v_cvt_pk_bf16_f32 v95, v86, v87
	v_cvt_pk_bf16_f32 v28, v28, v29
	v_cvt_pk_bf16_f32 v29, v30, v31
	v_cvt_pk_bf16_f32 v24, v24, v25
	v_cvt_pk_bf16_f32 v25, v26, v27
	v_pk_fma_f32 v[18:19], v[46:47], v[96:97], v[18:19]
	v_cvt_pk_bf16_f32 v86, v100, v101
	v_cvt_pk_bf16_f32 v87, v88, v89
	v_cvt_pk_bf16_f32 v72, v72, v73
	v_cvt_pk_bf16_f32 v73, v90, v91
	v_cvt_pk_bf16_f32 v70, v70, v71
	v_cvt_pk_bf16_f32 v71, v92, v93
	v_cvt_pk_bf16_f32 v20, v20, v21
	v_cvt_pk_bf16_f32 v21, v22, v23
	v_cvt_pk_bf16_f32 v16, v16, v17
	global_store_dwordx2 v[76:77], v[94:95], off
	global_store_dwordx2 v[76:77], v[86:87], off offset:512
	global_store_dwordx2 v[76:77], v[72:73], off offset:1024
	global_store_dwordx2 v[76:77], v[70:71], off offset:1536
	global_store_dwordx2 v[78:79], v[28:29], off
	global_store_dwordx2 v[78:79], v[24:25], off offset:512
	global_store_dwordx2 v[78:79], v[20:21], off offset:1024
	v_lshlrev_b32_e32 v23, 16, v29
	v_lshlrev_b32_e32 v22, 16, v28
	v_and_b32_e32 v27, 0xffff0000, v29
	v_and_b32_e32 v26, 0xffff0000, v28
	v_lshlrev_b32_e32 v29, 16, v25
	v_lshlrev_b32_e32 v28, 16, v24
	v_and_b32_e32 v25, 0xffff0000, v25
	v_and_b32_e32 v24, 0xffff0000, v24
	v_cvt_pk_bf16_f32 v17, v18, v19
	v_lshlrev_b32_e32 v18, 16, v20
	v_and_b32_e32 v19, 0xffff0000, v20
	v_lshlrev_b32_e32 v20, 16, v16
	v_lshlrev_b32_e32 v30, 16, v21
	v_pk_mul_f32 v[70:71], v[26:27], v[26:27]
	v_pk_mul_f32 v[72:73], v[24:25], v[24:25]
	global_store_dwordx2 v[78:79], v[16:17], off offset:1536
	v_and_b32_e32 v79, 0xffff0000, v16
	v_and_b32_e32 v31, 0xffff0000, v21
	v_mul_f32_e32 v21, v18, v18
	v_mul_f32_e32 v77, v19, v19
	v_mul_f32_e32 v78, v30, v30
	v_mov_b32_e32 v76, v20
	v_mov_b32_e32 v88, v22
	v_mov_b32_e32 v89, v26
	v_mov_b32_e32 v26, v23
	v_mov_b32_e32 v90, v28
	v_mov_b32_e32 v91, v24
	v_mov_b32_e32 v24, v29
	v_pk_fma_f32 v[22:23], v[22:23], v[22:23], v[70:71]
	v_pk_fma_f32 v[28:29], v[28:29], v[28:29], v[72:73]
	v_lshlrev_b32_e32 v16, 16, v17
	v_and_b32_e32 v17, 0xffff0000, v17
	v_pk_fma_f32 v[70:71], v[30:31], v[30:31], v[78:79] op_sel_hi:[1,1,0]
	v_pk_add_f32 v[72:73], v[20:21], v[76:77]
	v_pk_add_f32 v[22:23], v[22:23], v[22:23] op_sel_hi:[0,1]
	v_pk_add_f32 v[28:29], v[28:29], v[28:29] op_sel_hi:[0,1]
	v_mul_f32_e32 v86, v20, v20
	v_mul_f32_e32 v70, v79, v79
	v_mov_b32_e32 v87, v73
	v_mul_f32_e32 v22, v16, v16
	v_mul_f32_e32 v28, v17, v17
	v_pk_add_f32 v[70:71], v[86:87], v[70:71]
	v_pk_add_f32 v[22:23], v[22:23], v[28:29]
	v_mov_b32_e32 v21, v79
	v_pk_add_f32 v[22:23], v[70:71], v[22:23]
	s_nop 0
	v_add_f32_e32 v22, v22, v23
	ds_bpermute_b32 v23, v69, v22
	s_waitcnt lgkmcnt(0)
	v_add_f32_e32 v22, v22, v23
	ds_bpermute_b32 v23, v80, v22
	s_waitcnt lgkmcnt(0)
	v_add_f32_e32 v22, v22, v23
	ds_bpermute_b32 v23, v81, v22
	s_waitcnt lgkmcnt(0)
	v_add_f32_e32 v22, v22, v23
	ds_bpermute_b32 v23, v82, v22
	s_waitcnt lgkmcnt(0)
	v_add_f32_e32 v22, v22, v23
	ds_bpermute_b32 v23, v83, v22
	s_waitcnt lgkmcnt(0)
	v_add_f32_e32 v22, v22, v23
	ds_bpermute_b32 v23, v84, v22
	s_waitcnt lgkmcnt(0)
	v_add_f32_e32 v22, v22, v23
	v_fmamk_f32 v22, v22, 0x3a800000, v68
	v_mul_f32_e32 v23, 0x4b800000, v22
	v_cmp_gt_f32_e32 vcc, s24, v22
	s_nop 1
	v_cndmask_b32_e32 v22, v22, v23, vcc
	v_rsq_f32_e32 v22, v22
	s_nop 0
	v_mul_f32_e32 v23, 0x45800000, v22
	v_cndmask_b32_e32 v22, v22, v23, vcc
	v_pk_mul_f32 v[28:29], v[22:23], v[88:89] op_sel_hi:[0,1]
	v_pk_mul_f32 v[26:27], v[22:23], v[26:27] op_sel_hi:[0,1]
	v_pk_mul_f32 v[70:71], v[22:23], v[90:91] op_sel_hi:[0,1]
	v_pk_mul_f32 v[24:25], v[22:23], v[24:25] op_sel_hi:[0,1]
	v_pk_mul_f32 v[18:19], v[22:23], v[18:19] op_sel_hi:[0,1]
	v_pk_mul_f32 v[30:31], v[22:23], v[30:31] op_sel_hi:[0,1]
	v_pk_mul_f32 v[20:21], v[22:23], v[20:21] op_sel_hi:[0,1]
	v_pk_mul_f32 v[16:17], v[22:23], v[16:17] op_sel_hi:[0,1]
	v_pk_fma_f32 v[22:23], v[50:51], v[26:27], v[2:3]
	v_pk_fma_f32 v[26:27], v[52:53], v[28:29], v[0:1]
	v_pk_fma_f32 v[24:25], v[54:55], v[24:25], v[6:7]
	v_pk_fma_f32 v[28:29], v[56:57], v[70:71], v[4:5]
	v_pk_fma_f32 v[30:31], v[58:59], v[30:31], v[10:11]
	v_pk_fma_f32 v[18:19], v[60:61], v[18:19], v[8:9]
	v_pk_fma_f32 v[16:17], v[62:63], v[16:17], v[14:15]
	v_pk_fma_f32 v[20:21], v[64:65], v[20:21], v[12:13]
	v_cvt_pk_bf16_f32 v26, v26, v27
	v_cvt_pk_bf16_f32 v27, v22, v23
	v_cvt_pk_bf16_f32 v22, v28, v29
	v_cvt_pk_bf16_f32 v23, v24, v25
	v_cvt_pk_bf16_f32 v18, v18, v19
	v_cvt_pk_bf16_f32 v19, v30, v31
	v_cvt_pk_bf16_f32 v20, v20, v21
	v_cvt_pk_bf16_f32 v21, v16, v17
	global_store_dwordx2 v[74:75], v[26:27], off
	global_store_dwordx2 v[74:75], v[22:23], off offset:512
	global_store_dwordx2 v[74:75], v[18:19], off offset:1024
	global_store_dwordx2 v[74:75], v[20:21], off offset:1536
	s_cbranch_scc1 .LBB0_764

.LBB0_977:
	s_cmp_lt_i32 s48, 11
	s_cselect_b64 s[6:7], -1, 0
	s_add_u32 s40, s46, 0xc000000
	s_addc_u32 s41, s47, 0
	s_and_b64 s[6:7], s[6:7], s[4:5]
	v_mov_b32_e32 v90, v190
	s_andn2_b64 vcc, exec, s[6:7]
	s_cbranch_vccnz .LBB0_981
	s_lshl_b32 s4, s3, 3
	s_abs_i32 s5, s4
	v_cvt_f32_u32_e32 v0, s5
	s_sub_i32 s8, 0, s5
	s_ashr_i32 s4, s4, 31
	s_mov_b32 s17, 0
	v_rcp_iflag_f32_e32 v0, v0
	s_nop 0
	v_mul_f32_e32 v0, 0x4f7ffffe, v0
	v_cvt_u32_f32_e32 v0, v0
	s_nop 0
	v_readfirstlane_b32 s9, v0
	s_mul_i32 s8, s8, s9
	s_mul_hi_u32 s8, s9, s8
	s_add_i32 s9, s9, s8
	s_lshr_b32 s8, s9, 17
	s_mul_i32 s9, s8, s5
	s_sub_i32 s9, 0x8000, s9
	s_add_i32 s10, s8, 1
	s_sub_i32 s11, s9, s5
	s_cmp_ge_u32 s9, s5
	s_cselect_b32 s8, s10, s8
	s_cselect_b32 s9, s11, s9
	s_add_i32 s10, s8, 1
	s_cmp_ge_u32 s9, s5
	s_cselect_b32 s5, s10, s8
	s_xor_b32 s5, s5, s4
	s_sub_i32 s16, s5, s4
	s_cmp_lt_i32 s16, 1
	s_cbranch_scc1 .LBB0_981
	s_load_dwordx2 s[4:5], s[0:1], 0x28
	s_load_dwordx2 s[12:13], s[0:1], 0x60
	v_lshlrev_b32_e32 v0, 2, v90
	v_and_b32_e32 v91, 0xfc, v0
	v_lshlrev_b32_e32 v32, 2, v91
	s_waitcnt lgkmcnt(0)
	s_add_u32 s8, s4, 0x3000
	s_addc_u32 s9, s5, 0
	s_add_u32 s10, s4, 0x4000
	s_addc_u32 s11, s5, 0
	s_lshl_b32 s4, s2, 3
	v_readlane_b32 s5, v247, 2
	s_add_i32 s4, s5, s4
	s_mul_i32 s4, s16, s4
	s_ashr_i32 s5, s4, 31
	s_lshr_b32 s14, s5, 19
	s_add_i32 s14, s4, s14
	s_ashr_i32 s14, s14, 13
	s_ashr_i32 s15, s14, 31
	s_mul_hi_i32 s18, s14, 0x6000
	s_mul_i32 s19, s14, 0x6000
	s_lshl_b64 s[14:15], s[14:15], 13
	s_add_u32 s20, s46, s14
	s_addc_u32 s21, s47, s15
	s_add_u32 s14, s46, s14
	s_addc_u32 s15, s47, s15
	s_add_u32 s22, s46, s19
	s_addc_u32 s23, s47, s18
	v_mov_b32_e32 v33, 0
	v_lshl_add_u64 v[16:17], s[22:23], 0, v[32:33]
	s_mov_b32 s22, 0x105000
	v_add_co_u32_e32 v0, vcc, s22, v16
	v_lshl_add_u64 v[18:19], s[20:21], 0, v[32:33]
	s_nop 0
	v_addc_co_u32_e32 v1, vcc, 0, v17, vcc
	s_mov_b32 s20, 0x131000
	v_add_co_u32_e32 v12, vcc, s20, v18
	global_load_dwordx4 v[0:3], v[0:1], off nt
	s_nop 0
	global_load_dwordx4 v[4:7], v32, s[8:9]
	global_load_dwordx4 v[8:11], v32, s[12:13]
	v_addc_co_u32_e32 v13, vcc, 0, v19, vcc
	global_load_dwordx4 v[12:15], v[12:13], off nt
	s_mov_b32 s20, 0x119000
	v_add_co_u32_e32 v20, vcc, s20, v16
	s_mov_b64 s[20:21], 0x105000
	s_nop 0
	v_addc_co_u32_e32 v21, vcc, 0, v17, vcc
	global_load_dwordx4 v[42:45], v[20:21], off nt
	v_lshl_add_u64 v[20:21], v[16:17], 0, s[20:21]
	s_mov_b64 s[20:21], 0x131000
	v_or_b32_e32 v22, 0x400, v32
	v_lshl_add_u64 v[18:19], v[18:19], 0, s[20:21]
	global_load_dwordx4 v[46:49], v32, s[10:11]
	global_load_dwordx4 v[50:53], v[20:21], off offset:1024 nt
	global_load_dwordx4 v[54:57], v22, s[8:9]
	global_load_dwordx4 v[58:61], v[18:19], off offset:1024 nt
	global_load_dwordx4 v[62:65], v32, s[12:13] offset:1024
	s_mov_b64 s[20:21], 0x119000
	v_lshl_add_u64 v[16:17], v[16:17], 0, s[20:21]
	global_load_dwordx4 v[66:69], v[16:17], off offset:1024 nt
	global_load_dwordx4 v[70:73], v22, s[10:11]
	global_load_dwordx4 v[74:77], v[20:21], off offset:2048 nt
	v_or_b32_e32 v22, 0x800, v32
	global_load_dwordx4 v[78:81], v22, s[8:9]
	global_load_dwordx4 v[82:85], v[18:19], off offset:2048 nt
	global_load_dwordx4 v[86:89], v32, s[12:13] offset:2048
	global_load_dwordx4 v[92:95], v[16:17], off offset:2048 nt
	global_load_dwordx4 v[96:99], v22, s[10:11]
	global_load_dwordx4 v[100:103], v[20:21], off offset:3072 nt
	v_or_b32_e32 v20, 0xc00, v32
	global_load_dwordx4 v[104:107], v20, s[8:9]
	global_load_dwordx4 v[108:111], v[18:19], off offset:3072 nt
	global_load_dwordx4 v[112:115], v32, s[12:13] offset:3072
	global_load_dwordx4 v[116:119], v[16:17], off offset:3072 nt
	global_load_dwordx4 v[120:123], v20, s[10:11]
	s_mov_b64 s[8:9], 0x130000
	v_lshl_add_u64 v[16:17], s[14:15], 0, v[32:33]
	s_mov_b32 s12, 0x130000
	v_lshl_add_u64 v[28:29], v[16:17], 0, s[8:9]
	s_add_u32 s8, s46, s19
	v_add_co_u32_e32 v30, vcc, s12, v16
	s_addc_u32 s9, s47, s18
	s_nop 0
	v_addc_co_u32_e32 v31, vcc, 0, v17, vcc
	v_lshl_add_u64 v[16:17], s[8:9], 0, v[32:33]
	s_mov_b32 s8, 0x118000
	s_mov_b64 s[10:11], 0x118000
	v_add_co_u32_e32 v126, vcc, s8, v16
	v_lshl_add_u64 v[124:125], v[16:17], 0, s[10:11]
	s_nop 0
	v_addc_co_u32_e32 v127, vcc, 0, v17, vcc
	v_lshlrev_b32_e32 v32, 1, v91
	s_add_i32 s13, s4, 1
	s_lshl_b64 s[4:5], s[4:5], 11
	s_add_u32 s8, s46, s4
	s_addc_u32 s9, s47, s5
	s_add_u32 s10, s38, s4
	s_addc_u32 s11, s39, s5
	s_mov_b32 s12, 0x3a800000
	s_mov_b32 s18, 0x800000
	s_brev_b32 s19, 16
	s_brev_b32 s20, 48
	s_waitcnt vmcnt(0)
	v_pk_mul_f32 v[38:39], v[2:3], v[6:7]
	v_pk_mul_f32 v[40:41], v[0:1], v[4:5]
	v_pk_add_f32 v[14:15], v[14:15], 1.0 op_sel_hi:[1,0]
	v_pk_add_f32 v[12:13], v[12:13], 1.0 op_sel_hi:[1,0]
	v_pk_mul_f32 v[34:35], v[10:11], v[14:15]
	v_pk_mul_f32 v[36:37], v[8:9], v[12:13]
	global_load_dwordx4 v[0:3], v[28:29], off offset:1024 nt
	global_load_dwordx4 v[4:7], v[28:29], off offset:2048 nt
	global_load_dwordx4 v[8:11], v[124:125], off offset:1024 nt
	global_load_dwordx4 v[12:15], v[124:125], off offset:2048 nt
	global_load_dwordx4 v[16:19], v[30:31], off nt
	global_load_dwordx4 v[20:23], v[28:29], off offset:3072 nt
	global_load_dwordx4 v[24:27], v[126:127], off nt
	s_nop 0
	global_load_dwordx4 v[28:31], v[124:125], off offset:3072 nt
	v_pk_add_f32 v[44:45], v[44:45], 1.0 op_sel_hi:[1,0]
	v_pk_add_f32 v[124:125], v[42:43], 1.0 op_sel_hi:[1,0]
	v_pk_mul_f32 v[42:43], v[48:49], v[44:45]
	v_pk_mul_f32 v[48:49], v[50:51], v[54:55]
	v_pk_add_f32 v[50:51], v[60:61], 1.0 op_sel_hi:[1,0]
	v_pk_mul_f32 v[44:45], v[46:47], v[124:125]
	v_pk_mul_f32 v[50:51], v[64:65], v[50:51]
	v_pk_add_f32 v[64:65], v[82:83], 1.0 op_sel_hi:[1,0]
	v_pk_mul_f32 v[46:47], v[52:53], v[56:57]
	v_pk_mul_f32 v[64:65], v[86:87], v[64:65]
	v_mbcnt_lo_u32_b32 v86, -1, 0
	v_pk_add_f32 v[52:53], v[58:59], 1.0 op_sel_hi:[1,0]
	v_mbcnt_hi_u32_b32 v86, -1, v86
	v_pk_mul_f32 v[52:53], v[62:63], v[52:53]
	v_pk_add_f32 v[62:63], v[84:85], 1.0 op_sel_hi:[1,0]
	v_and_b32_e32 v87, 64, v86
	v_pk_mul_f32 v[62:63], v[88:89], v[62:63]
	v_add_u32_e32 v87, 64, v87
	v_xor_b32_e32 v88, 1, v86
	v_cmp_lt_i32_e32 vcc, v88, v87
	v_pk_add_f32 v[54:55], v[68:69], 1.0 op_sel_hi:[1,0]
	v_pk_add_f32 v[56:57], v[66:67], 1.0 op_sel_hi:[1,0]
	v_cndmask_b32_e32 v88, v86, v88, vcc
	v_lshlrev_b32_e32 v91, 2, v88
	v_xor_b32_e32 v88, 2, v86
	v_cmp_lt_i32_e32 vcc, v88, v87
	v_pk_mul_f32 v[54:55], v[72:73], v[54:55]
	v_pk_mul_f32 v[72:73], v[100:101], v[104:105]
	v_cndmask_b32_e32 v88, v86, v88, vcc
	v_lshlrev_b32_e32 v104, 2, v88
	v_xor_b32_e32 v88, 4, v86
	v_cmp_lt_i32_e32 vcc, v88, v87
	v_pk_mul_f32 v[56:57], v[70:71], v[56:57]
	v_pk_mul_f32 v[70:71], v[102:103], v[106:107]
	v_cndmask_b32_e32 v88, v86, v88, vcc
	v_lshlrev_b32_e32 v105, 2, v88
	v_xor_b32_e32 v88, 8, v86
	v_cmp_lt_i32_e32 vcc, v88, v87
	v_pk_mul_f32 v[58:59], v[76:77], v[80:81]
	v_pk_mul_f32 v[60:61], v[74:75], v[78:79]
	v_cndmask_b32_e32 v88, v86, v88, vcc
	v_lshlrev_b32_e32 v106, 2, v88
	v_xor_b32_e32 v88, 16, v86
	v_cmp_lt_i32_e32 vcc, v88, v87
	v_pk_add_f32 v[66:67], v[94:95], 1.0 op_sel_hi:[1,0]
	v_pk_add_f32 v[68:69], v[92:93], 1.0 op_sel_hi:[1,0]
	v_cndmask_b32_e32 v88, v86, v88, vcc
	v_lshlrev_b32_e32 v107, 2, v88
	v_xor_b32_e32 v88, 32, v86
	v_cmp_lt_i32_e32 vcc, v88, v87
	v_pk_add_f32 v[74:75], v[110:111], 1.0 op_sel_hi:[1,0]
	v_pk_add_f32 v[76:77], v[108:109], 1.0 op_sel_hi:[1,0]
	v_cndmask_b32_e32 v86, v86, v88, vcc
	v_pk_add_f32 v[78:79], v[118:119], 1.0 op_sel_hi:[1,0]
	v_pk_add_f32 v[80:81], v[116:117], 1.0 op_sel_hi:[1,0]
	v_lshl_add_u64 v[82:83], s[38:39], 0, v[32:33]
	v_lshl_add_u64 v[84:85], s[36:37], 0, v[32:33]
	v_lshlrev_b32_e32 v108, 2, v86
	v_lshl_add_u64 v[86:87], s[58:59], 0, v[32:33]
	v_lshl_add_u64 v[88:89], s[40:41], 0, v[32:33]
	v_and_b32_e32 v32, 63, v90
	v_pk_mul_f32 v[66:67], v[98:99], v[66:67]
	v_pk_mul_f32 v[68:69], v[96:97], v[68:69]
	v_pk_mul_f32 v[74:75], v[114:115], v[74:75]
	v_pk_mul_f32 v[76:77], v[112:113], v[76:77]
	v_pk_mul_f32 v[78:79], v[122:123], v[78:79]
	v_pk_mul_f32 v[80:81], v[120:121], v[80:81]
	v_lshlrev_b32_e32 v32, 3, v32
	v_mov_b32_e32 v90, 0x358637bd
.LBB0_980:
	v_lshl_add_u64 v[94:95], s[8:9], 0, v[32:33]
	v_add_co_u32_e64 v98, s[4:5], s19, v94
	s_add_i32 s14, s13, s17
	s_nop 0
	v_addc_co_u32_e64 v99, s[4:5], 0, v95, s[4:5]
	v_add_co_u32_e32 v96, vcc, 0x4000000, v94
	v_add_co_u32_e64 v100, s[4:5], s20, v94
	v_lshl_add_u64 v[92:93], s[10:11], 0, v[32:33]
	s_ashr_i32 s15, s14, 31
	v_addc_co_u32_e64 v101, s[4:5], 0, v95, s[4:5]
	v_addc_co_u32_e32 v97, vcc, 0, v95, vcc
	global_load_dwordx2 v[110:111], v[92:93], off nt
	global_load_dwordx2 v[112:113], v[92:93], off offset:512 nt
	global_load_dwordx2 v[114:115], v[92:93], off offset:1024 nt
	global_load_dwordx2 v[116:117], v[92:93], off offset:1536 nt
	s_lshl_b64 s[4:5], s[14:15], 11
	global_load_dwordx2 v[118:119], v[96:97], off offset:1536 nt
	global_load_dwordx2 v[120:121], v[96:97], off nt
	global_load_dwordx2 v[122:123], v[96:97], off offset:512 nt
	global_load_dwordx2 v[124:125], v[96:97], off offset:1024 nt
	v_lshl_add_u64 v[126:127], v[84:85], 0, s[4:5]
	v_lshl_add_u64 v[102:103], v[82:83], 0, s[4:5]
	global_load_dwordx2 v[128:129], v[102:103], off nt
	global_load_dwordx2 v[130:131], v[102:103], off offset:512 nt
	global_load_dwordx2 v[132:133], v[102:103], off offset:1024 nt
	global_load_dwordx2 v[134:135], v[102:103], off offset:1536 nt
	global_load_dwordx2 v[136:137], v[126:127], off offset:1536 nt
	global_load_dwordx2 v[138:139], v[126:127], off nt
	global_load_dwordx2 v[140:141], v[126:127], off offset:512 nt
	s_nop 0
	global_load_dwordx2 v[126:127], v[126:127], off offset:1024 nt
	v_lshl_add_u64 v[94:95], v[86:87], 0, s[4:5]
	v_lshl_add_u64 v[96:97], v[88:89], 0, s[4:5]
	s_add_i32 s17, s17, 2
	s_add_u32 s8, s8, 0x1000
	s_addc_u32 s9, s9, 0
	s_add_u32 s10, s10, 0x1000
	s_addc_u32 s11, s11, 0
	s_cmp_lt_i32 s17, s16
	s_waitcnt vmcnt(15)
	v_lshlrev_b32_e32 v142, 16, v110
	v_and_b32_e32 v143, 0xffff0000, v110
	s_waitcnt vmcnt(11)
	v_lshlrev_b32_e32 v151, 16, v118
	s_waitcnt vmcnt(10)
	v_lshlrev_b32_e32 v154, 16, v120
	v_and_b32_e32 v155, 0xffff0000, v120
	v_lshlrev_b32_e32 v120, 16, v121
	v_and_b32_e32 v121, 0xffff0000, v121
	s_waitcnt vmcnt(9)
	v_lshlrev_b32_e32 v157, 16, v123
	v_lshlrev_b32_e32 v156, 16, v122
	v_and_b32_e32 v123, 0xffff0000, v123
	v_and_b32_e32 v122, 0xffff0000, v122
	s_waitcnt vmcnt(8)
	v_lshlrev_b32_e32 v158, 16, v124
	v_and_b32_e32 v159, 0xffff0000, v124
	v_lshlrev_b32_e32 v124, 16, v125
	v_and_b32_e32 v125, 0xffff0000, v125
	s_waitcnt vmcnt(3)
	v_lshlrev_b32_e32 v169, 16, v136
	v_mul_f32_e32 v150, v121, v121
	v_pk_mul_f32 v[172:173], v[122:123], v[122:123]
	v_mul_f32_e32 v168, v155, v155
	v_mov_b32_e32 v175, v151
	v_mul_f32_e32 v174, v125, v125
	v_mov_b32_e32 v176, v156
	v_mov_b32_e32 v177, v122
	v_mov_b32_e32 v122, v157
	s_waitcnt vmcnt(2)
	v_lshlrev_b32_e32 v178, 16, v138
	v_and_b32_e32 v179, 0xffff0000, v138
	v_lshlrev_b32_e32 v138, 16, v139
	v_and_b32_e32 v139, 0xffff0000, v139
	s_waitcnt vmcnt(1)
	v_lshlrev_b32_e32 v181, 16, v141
	v_lshlrev_b32_e32 v180, 16, v140
	v_and_b32_e32 v141, 0xffff0000, v141
	v_and_b32_e32 v140, 0xffff0000, v140
	v_pk_fma_f32 v[184:185], v[120:121], v[120:121], v[150:151] op_sel_hi:[1,1,0]
	v_pk_fma_f32 v[156:157], v[156:157], v[156:157], v[172:173]
	v_pk_fma_f32 v[172:173], v[154:155], v[154:155], v[168:169] op_sel_hi:[1,1,0]
	v_and_b32_e32 v153, 0xffff0000, v118
	v_lshlrev_b32_e32 v118, 16, v119
	v_and_b32_e32 v119, 0xffff0000, v119
	v_and_b32_e32 v171, 0xffff0000, v136
	v_mul_f32_e32 v170, v159, v159
	v_pk_fma_f32 v[188:189], v[124:125], v[124:125], v[174:175] op_sel_hi:[1,1,0]
	v_mul_f32_e32 v168, v139, v139
	v_pk_mul_f32 v[192:193], v[140:141], v[140:141]
	v_mul_f32_e32 v194, v179, v179
	v_mov_b32_e32 v195, v169
	v_mov_b32_e32 v150, v172
	v_mov_b32_e32 v174, v184
	v_mul_f32_e32 v109, v153, v153
	v_mul_f32_e32 v191, v118, v118
	v_mul_f32_e32 v197, v119, v119
	v_mov_b32_e32 v152, v151
	s_waitcnt vmcnt(0)
	v_lshlrev_b32_e32 v182, 16, v126
	v_and_b32_e32 v183, 0xffff0000, v126
	v_lshlrev_b32_e32 v126, 16, v127
	v_and_b32_e32 v127, 0xffff0000, v127
	v_pk_fma_f32 v[186:187], v[158:159], v[158:159], v[170:171] op_sel_hi:[1,1,0]
	v_mov_b32_e32 v200, v180
	v_mov_b32_e32 v201, v140
	v_mov_b32_e32 v140, v181
	v_pk_add_f32 v[172:173], v[172:173], v[184:185]
	v_pk_add_f32 v[156:157], v[156:157], v[156:157] op_sel:[0,1] op_sel_hi:[1,0]
	v_pk_fma_f32 v[184:185], v[138:139], v[138:139], v[168:169] op_sel_hi:[1,1,0]
	v_pk_fma_f32 v[180:181], v[180:181], v[180:181], v[192:193]
	v_pk_fma_f32 v[192:193], v[178:179], v[178:179], v[194:195] op_sel_hi:[1,1,0]
	v_pk_mul_f32 v[150:151], v[150:151], v[174:175]
	v_lshlrev_b32_e32 v136, 16, v137
	v_and_b32_e32 v137, 0xffff0000, v137
	v_mul_f32_e32 v196, v183, v183
	v_mul_f32_e32 v198, v127, v127
	v_mov_b32_e32 v187, v191
	v_mov_b32_e32 v189, v197
	v_mov_b32_e32 v157, v109
	v_mov_b32_e32 v168, v192
	v_mov_b32_e32 v194, v184
	v_mov_b32_e32 v173, v151
	v_mul_f32_e32 v202, v171, v171
	v_mul_f32_e32 v203, v136, v136
	v_mul_f32_e32 v204, v137, v137
	v_pk_fma_f32 v[196:197], v[182:183], v[182:183], v[196:197] op_sel_hi:[1,1,0]
	v_pk_fma_f32 v[198:199], v[126:127], v[126:127], v[198:199] op_sel_hi:[1,1,0]
	v_pk_add_f32 v[174:175], v[186:187], v[188:189]
	v_pk_add_f32 v[184:185], v[192:193], v[184:185]
	v_pk_add_f32 v[180:181], v[180:181], v[180:181] op_sel:[0,1] op_sel_hi:[1,0]
	v_pk_mul_f32 v[150:151], v[168:169], v[194:195]
	v_pk_add_f32 v[156:157], v[172:173], v[156:157]
	v_mov_b32_e32 v197, v203
	v_mov_b32_e32 v199, v204
	v_mov_b32_e32 v181, v202
	v_mov_b32_e32 v185, v151
	v_pk_add_f32 v[150:151], v[156:157], v[174:175]
	v_mov_b32_e32 v170, v169
	v_pk_add_f32 v[168:169], v[196:197], v[198:199]
	v_pk_add_f32 v[156:157], v[184:185], v[180:181]
	v_add_f32_e32 v109, v150, v151
	v_pk_add_f32 v[150:151], v[156:157], v[168:169]
	ds_bpermute_b32 v157, v91, v109
	v_mov_b32_e32 v156, v150
	v_lshlrev_b32_e32 v110, 16, v111
	v_and_b32_e32 v111, 0xffff0000, v111
	v_lshlrev_b32_e32 v144, 16, v112
	s_waitcnt lgkmcnt(0)
	v_add_f32_e32 v109, v109, v157
	ds_bpermute_b32 v150, v104, v109
	v_and_b32_e32 v145, 0xffff0000, v112
	v_lshlrev_b32_e32 v112, 16, v113
	v_and_b32_e32 v113, 0xffff0000, v113
	v_lshlrev_b32_e32 v146, 16, v114
	s_waitcnt lgkmcnt(0)
	v_add_f32_e32 v109, v109, v150
	ds_bpermute_b32 v150, v105, v109
	v_and_b32_e32 v147, 0xffff0000, v114
	v_lshlrev_b32_e32 v114, 16, v115
	v_and_b32_e32 v115, 0xffff0000, v115
	v_lshlrev_b32_e32 v148, 16, v116
	s_waitcnt lgkmcnt(0)
	v_add_f32_e32 v109, v109, v150
	ds_bpermute_b32 v150, v106, v109
	v_and_b32_e32 v149, 0xffff0000, v116
	v_lshlrev_b32_e32 v116, 16, v117
	v_and_b32_e32 v117, 0xffff0000, v117
	v_lshlrev_b32_e32 v160, 16, v128
	s_waitcnt lgkmcnt(0)
	v_add_f32_e32 v109, v109, v150
	ds_bpermute_b32 v150, v107, v109
	v_and_b32_e32 v161, 0xffff0000, v128
	v_lshlrev_b32_e32 v128, 16, v129
	v_and_b32_e32 v129, 0xffff0000, v129
	v_lshlrev_b32_e32 v162, 16, v130
	s_waitcnt lgkmcnt(0)
	v_add_f32_e32 v109, v109, v150
	ds_bpermute_b32 v150, v108, v109
	v_and_b32_e32 v163, 0xffff0000, v130
	v_lshlrev_b32_e32 v130, 16, v131
	v_and_b32_e32 v131, 0xffff0000, v131
	v_lshlrev_b32_e32 v164, 16, v132
	s_waitcnt lgkmcnt(0)
	v_add_f32_e32 v109, v109, v150
	v_fmamk_f32 v109, v109, 0x3a800000, v90
	v_mul_f32_e32 v150, 0x4b800000, v109
	v_cmp_gt_f32_e32 vcc, s18, v109
	v_and_b32_e32 v165, 0xffff0000, v132
	v_lshlrev_b32_e32 v132, 16, v133
	v_cndmask_b32_e32 v109, v109, v150, vcc
	v_rsq_f32_e32 v109, v109
	v_and_b32_e32 v133, 0xffff0000, v133
	v_lshlrev_b32_e32 v166, 16, v134
	v_and_b32_e32 v167, 0xffff0000, v134
	v_mul_f32_e32 v150, 0x45800000, v109
	v_cndmask_b32_e32 v150, v109, v150, vcc
	v_pk_mul_f32 v[154:155], v[150:151], v[154:155] op_sel_hi:[0,1]
	v_pk_mul_f32 v[120:121], v[150:151], v[120:121] op_sel_hi:[0,1]
	v_pk_mul_f32 v[168:169], v[150:151], v[176:177] op_sel_hi:[0,1]
	v_pk_mul_f32 v[122:123], v[150:151], v[122:123] op_sel_hi:[0,1]
	v_pk_mul_f32 v[158:159], v[150:151], v[158:159] op_sel_hi:[0,1]
	v_pk_mul_f32 v[124:125], v[150:151], v[124:125] op_sel_hi:[0,1]
	v_pk_mul_f32 v[152:153], v[150:151], v[152:153] op_sel_hi:[0,1]
	v_pk_mul_f32 v[118:119], v[150:151], v[118:119] op_sel_hi:[0,1]
	v_pk_fma_f32 v[110:111], v[38:39], v[120:121], v[110:111]
	v_pk_fma_f32 v[120:121], v[40:41], v[154:155], v[142:143]
	v_pk_fma_f32 v[112:113], v[46:47], v[122:123], v[112:113]
	v_pk_fma_f32 v[122:123], v[48:49], v[168:169], v[144:145]
	v_pk_fma_f32 v[114:115], v[58:59], v[124:125], v[114:115]
	v_pk_fma_f32 v[124:125], v[60:61], v[158:159], v[146:147]
	v_pk_fma_f32 v[116:117], v[70:71], v[118:119], v[116:117]
	v_pk_fma_f32 v[118:119], v[72:73], v[152:153], v[148:149]
	v_cvt_pk_bf16_f32 v120, v120, v121
	v_cvt_pk_bf16_f32 v121, v110, v111
	v_cvt_pk_bf16_f32 v110, v122, v123
	v_cvt_pk_bf16_f32 v111, v112, v113
	v_cvt_pk_bf16_f32 v112, v124, v125
	v_cvt_pk_bf16_f32 v113, v114, v115
	v_cvt_pk_bf16_f32 v114, v118, v119
	v_cvt_pk_bf16_f32 v115, v116, v117
	global_store_dwordx2 v[92:93], v[120:121], off
	global_store_dwordx2 v[92:93], v[110:111], off offset:512
	global_store_dwordx2 v[92:93], v[112:113], off offset:1024
	v_lshlrev_b32_e32 v119, 16, v121
	v_lshlrev_b32_e32 v118, 16, v120
	v_and_b32_e32 v121, 0xffff0000, v121
	v_and_b32_e32 v120, 0xffff0000, v120
	v_lshlrev_b32_e32 v123, 16, v111
	v_lshlrev_b32_e32 v122, 16, v110
	v_and_b32_e32 v111, 0xffff0000, v111
	v_and_b32_e32 v110, 0xffff0000, v110
	v_lshlrev_b32_e32 v116, 16, v112
	v_and_b32_e32 v117, 0xffff0000, v112
	global_store_dwordx2 v[92:93], v[114:115], off offset:1536
	v_lshlrev_b32_e32 v92, 16, v114
	v_lshlrev_b32_e32 v112, 16, v113
	v_pk_mul_f32 v[124:125], v[120:121], v[120:121]
	v_pk_mul_f32 v[142:143], v[110:111], v[110:111]
	v_and_b32_e32 v113, 0xffff0000, v113
	v_mul_f32_e32 v93, v116, v116
	v_mul_f32_e32 v145, v117, v117
	v_mul_f32_e32 v146, v112, v112
	v_mov_b32_e32 v144, v92
	v_mov_b32_e32 v152, v118
	v_mov_b32_e32 v153, v120
	v_mov_b32_e32 v120, v119
	v_mov_b32_e32 v154, v122
	v_mov_b32_e32 v155, v110
	v_mov_b32_e32 v110, v123
	v_pk_fma_f32 v[118:119], v[118:119], v[118:119], v[124:125]
	v_pk_fma_f32 v[122:123], v[122:123], v[122:123], v[142:143]
	v_and_b32_e32 v109, 0xffff0000, v114
	v_lshlrev_b32_e32 v114, 16, v115
	v_and_b32_e32 v115, 0xffff0000, v115
	v_pk_fma_f32 v[124:125], v[112:113], v[112:113], v[146:147] op_sel_hi:[1,1,0]
	v_pk_add_f32 v[142:143], v[92:93], v[144:145]
	v_pk_add_f32 v[118:119], v[118:119], v[118:119] op_sel_hi:[0,1]
	v_pk_add_f32 v[122:123], v[122:123], v[122:123] op_sel_hi:[0,1]
	v_mul_f32_e32 v148, v92, v92
	v_mul_f32_e32 v124, v109, v109
	v_mov_b32_e32 v149, v143
	v_mul_f32_e32 v118, v114, v114
	v_mul_f32_e32 v122, v115, v115
	v_pk_add_f32 v[124:125], v[148:149], v[124:125]
	v_pk_add_f32 v[118:119], v[118:119], v[122:123]
	v_mov_b32_e32 v93, v109
	v_pk_add_f32 v[118:119], v[124:125], v[118:119]
	v_lshlrev_b32_e32 v134, 16, v135
	v_mov_b32_e32 v157, v118
	v_mov_b32_e32 v118, v151
	v_pk_add_f32 v[118:119], v[156:157], v[118:119]
	ds_bpermute_b32 v123, v91, v119
	ds_bpermute_b32 v122, v91, v118
	v_and_b32_e32 v135, 0xffff0000, v135
	s_waitcnt lgkmcnt(0)
	v_pk_add_f32 v[118:119], v[118:119], v[122:123]
	ds_bpermute_b32 v123, v104, v119
	ds_bpermute_b32 v122, v104, v118
	s_waitcnt lgkmcnt(0)
	v_pk_add_f32 v[118:119], v[118:119], v[122:123]
	ds_bpermute_b32 v123, v105, v119
	ds_bpermute_b32 v122, v105, v118
	s_waitcnt lgkmcnt(0)
	v_pk_add_f32 v[118:119], v[118:119], v[122:123]
	ds_bpermute_b32 v123, v106, v119
	ds_bpermute_b32 v122, v106, v118
	s_waitcnt lgkmcnt(0)
	v_pk_add_f32 v[118:119], v[118:119], v[122:123]
	ds_bpermute_b32 v123, v107, v119
	ds_bpermute_b32 v122, v107, v118
	s_waitcnt lgkmcnt(0)
	v_pk_add_f32 v[118:119], v[118:119], v[122:123]
	ds_bpermute_b32 v123, v108, v119
	ds_bpermute_b32 v122, v108, v118
	s_waitcnt lgkmcnt(0)
	v_pk_add_f32 v[118:119], v[118:119], v[122:123]
	s_nop 0
	v_pk_fma_f32 v[118:119], v[118:119], s[12:13], v[90:91] op_sel_hi:[1,0,0]
	s_nop 0
	v_mul_f32_e32 v109, 0x4b800000, v119
	v_mul_f32_e32 v122, 0x4b800000, v118
	v_cmp_gt_f32_e32 vcc, s18, v118
	v_cmp_gt_f32_e64 s[4:5], s18, v119
	s_nop 0
	v_cndmask_b32_e32 v118, v118, v122, vcc
	v_cndmask_b32_e64 v109, v119, v109, s[4:5]
	v_rsq_f32_e32 v109, v109
	v_rsq_f32_e32 v119, v118
	v_mul_f32_e32 v118, 0x45800000, v109
	v_mul_f32_e32 v122, 0x45800000, v119
	v_cndmask_b32_e64 v118, v109, v118, s[4:5]
	v_cndmask_b32_e32 v122, v119, v122, vcc
	v_pk_mul_f32 v[124:125], v[118:119], v[152:153] op_sel_hi:[0,1]
	v_pk_mul_f32 v[120:121], v[118:119], v[120:121] op_sel_hi:[0,1]
	v_pk_mul_f32 v[142:143], v[118:119], v[154:155] op_sel_hi:[0,1]
	v_pk_mul_f32 v[110:111], v[118:119], v[110:111] op_sel_hi:[0,1]
	v_pk_mul_f32 v[116:117], v[118:119], v[116:117] op_sel_hi:[0,1]
	v_pk_mul_f32 v[112:113], v[118:119], v[112:113] op_sel_hi:[0,1]
	v_pk_mul_f32 v[92:93], v[118:119], v[92:93] op_sel_hi:[0,1]
	v_pk_mul_f32 v[114:115], v[118:119], v[114:115] op_sel_hi:[0,1]
	v_pk_mul_f32 v[118:119], v[122:123], v[178:179] op_sel_hi:[0,1]
	v_pk_mul_f32 v[138:139], v[122:123], v[138:139] op_sel_hi:[0,1]
	v_pk_mul_f32 v[144:145], v[122:123], v[200:201] op_sel_hi:[0,1]
	v_pk_mul_f32 v[140:141], v[122:123], v[140:141] op_sel_hi:[0,1]
	v_pk_mul_f32 v[146:147], v[122:123], v[182:183] op_sel_hi:[0,1]
	v_pk_mul_f32 v[126:127], v[122:123], v[126:127] op_sel_hi:[0,1]
	v_pk_mul_f32 v[148:149], v[122:123], v[170:171] op_sel_hi:[0,1]
	v_pk_mul_f32 v[122:123], v[122:123], v[136:137] op_sel_hi:[0,1]
	v_pk_fma_f32 v[136:137], v[34:35], v[120:121], v[18:19]
	v_pk_fma_f32 v[150:151], v[36:37], v[124:125], v[16:17]
	v_pk_fma_f32 v[152:153], v[50:51], v[110:111], v[2:3]
	v_pk_fma_f32 v[110:111], v[54:55], v[110:111], v[10:11]
	v_pk_fma_f32 v[156:157], v[62:63], v[112:113], v[6:7]
	v_pk_fma_f32 v[158:159], v[64:65], v[116:117], v[4:5]
	v_pk_fma_f32 v[168:169], v[74:75], v[114:115], v[22:23]
	v_pk_fma_f32 v[170:171], v[76:77], v[92:93], v[20:21]
	v_pk_fma_f32 v[114:115], v[78:79], v[114:115], v[30:31]
	v_pk_fma_f32 v[92:93], v[80:81], v[92:93], v[28:29]
	v_pk_fma_f32 v[128:129], v[38:39], v[138:139], v[128:129]
	v_pk_fma_f32 v[118:119], v[40:41], v[118:119], v[160:161]
	v_pk_fma_f32 v[130:131], v[46:47], v[140:141], v[130:131]
	v_pk_fma_f32 v[138:139], v[48:49], v[144:145], v[162:163]
	v_pk_fma_f32 v[126:127], v[58:59], v[126:127], v[132:133]
	v_pk_fma_f32 v[122:123], v[70:71], v[122:123], v[134:135]
	v_pk_fma_f32 v[134:135], v[72:73], v[148:149], v[166:167]
	v_pk_fma_f32 v[120:121], v[42:43], v[120:121], v[26:27]
	v_pk_fma_f32 v[124:125], v[44:45], v[124:125], v[24:25]
	v_pk_fma_f32 v[154:155], v[52:53], v[142:143], v[0:1]
	v_pk_fma_f32 v[142:143], v[56:57], v[142:143], v[8:9]
	v_pk_fma_f32 v[112:113], v[66:67], v[112:113], v[14:15]
	v_pk_fma_f32 v[116:117], v[68:69], v[116:117], v[12:13]
	v_pk_fma_f32 v[132:133], v[60:61], v[146:147], v[164:165]
	v_cvt_pk_bf16_f32 v140, v150, v151
	v_cvt_pk_bf16_f32 v141, v136, v137
	v_cvt_pk_bf16_f32 v137, v110, v111
	v_cvt_pk_bf16_f32 v110, v158, v159
	v_cvt_pk_bf16_f32 v111, v156, v157
	v_cvt_pk_bf16_f32 v92, v92, v93
	v_cvt_pk_bf16_f32 v93, v114, v115
	v_cvt_pk_bf16_f32 v114, v118, v119
	v_cvt_pk_bf16_f32 v115, v128, v129
	v_cvt_pk_bf16_f32 v118, v138, v139
	v_cvt_pk_bf16_f32 v119, v130, v131
	v_cvt_pk_bf16_f32 v129, v126, v127
	v_cvt_pk_bf16_f32 v126, v134, v135
	v_cvt_pk_bf16_f32 v127, v122, v123
	v_cvt_pk_bf16_f32 v124, v124, v125
	v_cvt_pk_bf16_f32 v125, v120, v121
	v_cvt_pk_bf16_f32 v120, v154, v155
	v_cvt_pk_bf16_f32 v121, v152, v153
	v_cvt_pk_bf16_f32 v136, v142, v143
	v_cvt_pk_bf16_f32 v116, v116, v117
	v_cvt_pk_bf16_f32 v117, v112, v113
	v_cvt_pk_bf16_f32 v112, v170, v171
	v_cvt_pk_bf16_f32 v113, v168, v169
	v_cvt_pk_bf16_f32 v128, v132, v133
	global_store_dwordx2 v[98:99], v[140:141], off
	global_store_dwordx2 v[100:101], v[124:125], off
	global_store_dwordx2 v[98:99], v[120:121], off offset:512
	global_store_dwordx2 v[100:101], v[136:137], off offset:512
	global_store_dwordx2 v[98:99], v[110:111], off offset:1024
	global_store_dwordx2 v[100:101], v[116:117], off offset:1024
	global_store_dwordx2 v[98:99], v[112:113], off offset:1536
	global_store_dwordx2 v[100:101], v[92:93], off offset:1536
	global_store_dwordx2 v[102:103], v[114:115], off
	global_store_dwordx2 v[102:103], v[118:119], off offset:512
	global_store_dwordx2 v[102:103], v[128:129], off offset:1024
	global_store_dwordx2 v[102:103], v[126:127], off offset:1536
	v_lshlrev_b32_e32 v103, 16, v115
	v_lshlrev_b32_e32 v102, 16, v114
	v_and_b32_e32 v111, 0xffff0000, v115
	v_and_b32_e32 v110, 0xffff0000, v114
	v_and_b32_e32 v115, 0xffff0000, v119
	v_and_b32_e32 v114, 0xffff0000, v118
	v_lshlrev_b32_e32 v92, 16, v128
	v_and_b32_e32 v93, 0xffff0000, v128
	v_lshlrev_b32_e32 v98, 16, v126
	v_lshlrev_b32_e32 v113, 16, v119
	v_lshlrev_b32_e32 v112, 16, v118
	v_lshlrev_b32_e32 v116, 16, v129
	v_pk_mul_f32 v[118:119], v[110:111], v[110:111]
	v_pk_mul_f32 v[120:121], v[114:115], v[114:115]
	v_and_b32_e32 v117, 0xffff0000, v129
	v_mul_f32_e32 v99, v92, v92
	v_mul_f32_e32 v123, v93, v93
	v_mul_f32_e32 v124, v116, v116
	v_mov_b32_e32 v122, v98
	v_mov_b32_e32 v128, v102
	v_mov_b32_e32 v129, v110
	v_mov_b32_e32 v110, v103
	v_mov_b32_e32 v130, v112
	v_mov_b32_e32 v131, v114
	v_mov_b32_e32 v114, v113
	v_pk_fma_f32 v[102:103], v[102:103], v[102:103], v[118:119]
	v_pk_fma_f32 v[112:113], v[112:113], v[112:113], v[120:121]
	v_and_b32_e32 v109, 0xffff0000, v126
	v_lshlrev_b32_e32 v100, 16, v127
	v_and_b32_e32 v101, 0xffff0000, v127
	v_pk_fma_f32 v[118:119], v[116:117], v[116:117], v[124:125] op_sel_hi:[1,1,0]
	v_pk_add_f32 v[120:121], v[98:99], v[122:123]
	v_pk_add_f32 v[102:103], v[102:103], v[102:103] op_sel_hi:[0,1]
	v_pk_add_f32 v[112:113], v[112:113], v[112:113] op_sel_hi:[0,1]
	v_mul_f32_e32 v126, v98, v98
	v_mul_f32_e32 v118, v109, v109
	v_mov_b32_e32 v127, v121
	v_mul_f32_e32 v102, v100, v100
	v_mul_f32_e32 v112, v101, v101
	v_pk_add_f32 v[118:119], v[126:127], v[118:119]
	v_pk_add_f32 v[102:103], v[102:103], v[112:113]
	v_mov_b32_e32 v99, v109
	v_pk_add_f32 v[102:103], v[118:119], v[102:103]
	s_nop 0
	v_add_f32_e32 v102, v102, v103
	ds_bpermute_b32 v103, v91, v102
	s_waitcnt lgkmcnt(0)
	v_add_f32_e32 v102, v102, v103
	ds_bpermute_b32 v103, v104, v102
	s_waitcnt lgkmcnt(0)
	v_add_f32_e32 v102, v102, v103
	ds_bpermute_b32 v103, v105, v102
	s_waitcnt lgkmcnt(0)
	v_add_f32_e32 v102, v102, v103
	ds_bpermute_b32 v103, v106, v102
	s_waitcnt lgkmcnt(0)
	v_add_f32_e32 v102, v102, v103
	ds_bpermute_b32 v103, v107, v102
	s_waitcnt lgkmcnt(0)
	v_add_f32_e32 v102, v102, v103
	ds_bpermute_b32 v103, v108, v102
	s_waitcnt lgkmcnt(0)
	v_add_f32_e32 v102, v102, v103
	v_fmamk_f32 v102, v102, 0x3a800000, v90
	v_mul_f32_e32 v103, 0x4b800000, v102
	v_cmp_gt_f32_e32 vcc, s18, v102
	s_nop 1
	v_cndmask_b32_e32 v102, v102, v103, vcc
	v_rsq_f32_e32 v102, v102
	s_nop 0
	v_mul_f32_e32 v103, 0x45800000, v102
	v_cndmask_b32_e32 v102, v102, v103, vcc
	v_pk_mul_f32 v[112:113], v[102:103], v[128:129] op_sel_hi:[0,1]
	v_pk_mul_f32 v[110:111], v[102:103], v[110:111] op_sel_hi:[0,1]
	v_pk_mul_f32 v[118:119], v[102:103], v[130:131] op_sel_hi:[0,1]
	v_pk_mul_f32 v[114:115], v[102:103], v[114:115] op_sel_hi:[0,1]
	v_pk_mul_f32 v[92:93], v[102:103], v[92:93] op_sel_hi:[0,1]
	v_pk_mul_f32 v[116:117], v[102:103], v[116:117] op_sel_hi:[0,1]
	v_pk_mul_f32 v[98:99], v[102:103], v[98:99] op_sel_hi:[0,1]
	v_pk_mul_f32 v[100:101], v[102:103], v[100:101] op_sel_hi:[0,1]
	v_pk_fma_f32 v[102:103], v[34:35], v[110:111], v[18:19]
	v_pk_fma_f32 v[120:121], v[36:37], v[112:113], v[16:17]
	v_pk_fma_f32 v[110:111], v[42:43], v[110:111], v[26:27]
	v_pk_fma_f32 v[112:113], v[44:45], v[112:113], v[24:25]
	v_pk_fma_f32 v[122:123], v[50:51], v[114:115], v[2:3]
	v_pk_fma_f32 v[124:125], v[52:53], v[118:119], v[0:1]
	v_pk_fma_f32 v[114:115], v[54:55], v[114:115], v[10:11]
	v_pk_fma_f32 v[118:119], v[56:57], v[118:119], v[8:9]
	v_pk_fma_f32 v[126:127], v[62:63], v[116:117], v[6:7]
	v_pk_fma_f32 v[128:129], v[64:65], v[92:93], v[4:5]
	v_pk_fma_f32 v[116:117], v[66:67], v[116:117], v[14:15]
	v_pk_fma_f32 v[92:93], v[68:69], v[92:93], v[12:13]
	v_pk_fma_f32 v[130:131], v[74:75], v[100:101], v[22:23]
	v_pk_fma_f32 v[132:133], v[76:77], v[98:99], v[20:21]
	v_pk_fma_f32 v[100:101], v[78:79], v[100:101], v[30:31]
	v_pk_fma_f32 v[98:99], v[80:81], v[98:99], v[28:29]
	v_cvt_pk_bf16_f32 v120, v120, v121
	v_cvt_pk_bf16_f32 v121, v102, v103
	v_cvt_pk_bf16_f32 v102, v112, v113
	v_cvt_pk_bf16_f32 v103, v110, v111
	v_cvt_pk_bf16_f32 v110, v124, v125
	v_cvt_pk_bf16_f32 v111, v122, v123
	v_cvt_pk_bf16_f32 v112, v118, v119
	v_cvt_pk_bf16_f32 v113, v114, v115
	v_cvt_pk_bf16_f32 v114, v128, v129
	v_cvt_pk_bf16_f32 v115, v126, v127
	v_cvt_pk_bf16_f32 v92, v92, v93
	v_cvt_pk_bf16_f32 v93, v116, v117
	v_cvt_pk_bf16_f32 v116, v132, v133
	v_cvt_pk_bf16_f32 v117, v130, v131
	v_cvt_pk_bf16_f32 v98, v98, v99
	v_cvt_pk_bf16_f32 v99, v100, v101
	global_store_dwordx2 v[94:95], v[120:121], off
	global_store_dwordx2 v[96:97], v[102:103], off
	global_store_dwordx2 v[94:95], v[110:111], off offset:512
	global_store_dwordx2 v[96:97], v[112:113], off offset:512
	global_store_dwordx2 v[94:95], v[114:115], off offset:1024
	global_store_dwordx2 v[96:97], v[92:93], off offset:1024
	global_store_dwordx2 v[94:95], v[116:117], off offset:1536
	global_store_dwordx2 v[96:97], v[98:99], off offset:1536
	s_cbranch_scc1 .LBB0_980

.LBB0_1495:
	s_cmp_lt_i32 s48, 17
	s_cselect_b64 s[4:5], -1, 0
	s_and_b64 s[4:5], s[4:5], s[0:1]
	v_mov_b32_e32 v58, v190
	s_andn2_b64 vcc, exec, s[4:5]
	s_cbranch_vccnz .LBB0_1499
	s_lshl_b32 s0, s3, 3
	s_abs_i32 s1, s0
	v_cvt_f32_u32_e32 v0, s1
	s_sub_i32 s6, 0, s1
	s_ashr_i32 s0, s0, 31
	s_mov_b32 s14, 0
	v_rcp_iflag_f32_e32 v0, v0
	s_nop 0
	v_mul_f32_e32 v0, 0x4f7ffffe, v0
	v_cvt_u32_f32_e32 v0, v0
	s_nop 0
	v_readfirstlane_b32 s7, v0
	s_mul_i32 s6, s6, s7
	s_mul_hi_u32 s6, s7, s6
	s_add_i32 s7, s7, s6
	s_lshr_b32 s6, s7, 17
	s_mul_i32 s7, s6, s1
	s_sub_i32 s7, 0x8000, s7
	s_add_i32 s8, s6, 1
	s_sub_i32 s9, s7, s1
	s_cmp_ge_u32 s7, s1
	s_cselect_b32 s6, s8, s6
	s_cselect_b32 s7, s9, s7
	s_add_i32 s8, s6, 1
	s_cmp_ge_u32 s7, s1
	s_cselect_b32 s1, s8, s6
	s_xor_b32 s1, s1, s0
	s_sub_i32 s11, s1, s0
	s_cmp_lt_i32 s11, 1
	s_cbranch_scc1 .LBB0_1499
	v_readlane_b32 s0, v247, 3
	v_readlane_b32 s1, v247, 4
	s_add_u32 s6, s0, 0x5000
	s_addc_u32 s7, s1, 0
	s_add_u32 s8, s0, 0x6000
	s_addc_u32 s9, s1, 0
	s_lshl_b32 s0, s2, 3
	v_readlane_b32 s1, v247, 2
	s_add_i32 s0, s1, s0
	s_mul_i32 s0, s11, s0
	s_ashr_i32 s1, s0, 31
	s_lshr_b32 s10, s1, 19
	s_add_i32 s10, s0, s10
	s_ashr_i32 s10, s10, 13
	v_lshlrev_b32_e32 v0, 2, v58
	s_mul_hi_i32 s13, s10, 0x6000
	s_mulk_i32 s10, 0x6000
	v_and_b32_e32 v22, 0xfc, v0
	s_add_u32 s12, s46, s10
	s_addc_u32 s13, s47, s13
	v_lshlrev_b32_e32 v16, 2, v22
	v_mov_b32_e32 v17, 0
	v_lshl_add_u64 v[0:1], s[12:13], 0, v[16:17]
	s_mov_b32 s10, 0x11b000
	v_add_co_u32_e32 v18, vcc, s10, v0
	s_mov_b32 s10, 0x11c000
	s_nop 0
	v_addc_co_u32_e32 v19, vcc, 0, v1, vcc
	v_add_co_u32_e32 v6, vcc, s10, v0
	s_mov_b64 s[12:13], 0x11a000
	s_nop 0
	v_addc_co_u32_e32 v7, vcc, 0, v1, vcc
	v_lshl_add_u64 v[2:3], v[0:1], 0, s[12:13]
	global_load_dwordx4 v[24:27], v[18:19], off offset:-4096 nt
	global_load_dwordx4 v[28:31], v16, s[6:7]
	s_mov_b64 s[12:13], 0x11c000
	global_load_dwordx4 v[32:35], v[6:7], off nt
	global_load_dwordx4 v[36:39], v[2:3], off offset:1024 nt
	v_or_b32_e32 v6, 0x400, v16
	v_lshl_add_u64 v[4:5], v[0:1], 0, s[12:13]
	global_load_dwordx4 v[40:43], v6, s[6:7]
	global_load_dwordx4 v[44:47], v[4:5], off offset:1024 nt
	global_load_dwordx4 v[48:51], v[2:3], off offset:2048 nt
	v_or_b32_e32 v7, 0x800, v16
	global_load_dwordx4 v[52:55], v7, s[6:7]
	global_load_dwordx4 v[60:63], v[4:5], off offset:2048 nt
	global_load_dwordx4 v[64:67], v[2:3], off offset:3072 nt
	v_or_b32_e32 v2, 0xc00, v16
	global_load_dwordx4 v[68:71], v2, s[6:7]
	global_load_dwordx4 v[72:75], v[4:5], off offset:3072 nt
	global_load_dwordx4 v[76:79], v16, s[8:9]
	global_load_dwordx4 v[80:83], v6, s[8:9]
	global_load_dwordx4 v[84:87], v7, s[8:9]
	global_load_dwordx4 v[88:91], v2, s[8:9]
	s_mov_b64 s[6:7], 0x11b000
	v_lshl_add_u64 v[20:21], v[0:1], 0, s[6:7]
	global_load_dwordx4 v[0:3], v[18:19], off nt
	global_load_dwordx4 v[4:7], v[20:21], off offset:1024 nt
	global_load_dwordx4 v[8:11], v[20:21], off offset:2048 nt
	global_load_dwordx4 v[12:15], v[20:21], off offset:3072 nt
	v_mbcnt_lo_u32_b32 v16, -1, 0
	v_mbcnt_hi_u32_b32 v94, -1, v16
	v_and_b32_e32 v16, 64, v94
	v_xor_b32_e32 v18, 1, v94
	v_add_u32_e32 v95, 64, v16
	v_cmp_lt_i32_e32 vcc, v18, v95
	s_add_i32 s15, s0, 1
	s_lshl_b64 s[0:1], s[0:1], 11
	v_cndmask_b32_e32 v16, v94, v18, vcc
	v_lshlrev_b32_e32 v59, 2, v16
	v_lshlrev_b32_e32 v16, 1, v22
	s_add_u32 s6, s46, s0
	s_addc_u32 s7, s47, s1
	s_waitcnt lgkmcnt(0)
	v_lshl_add_u64 v[18:19], s[38:39], 0, v[16:17]
	v_lshl_add_u64 v[20:21], s[36:37], 0, v[16:17]
	s_add_u32 s8, s38, s0
	s_addc_u32 s9, s39, s1
	s_mov_b32 s10, 0x3a800000
	s_mov_b32 s16, 0x800000
	s_brev_b32 s17, 48
	s_brev_b32 s18, 16
	s_waitcnt vmcnt(0)
	v_pk_mul_f32 v[22:23], v[26:27], v[30:31]
	v_pk_add_f32 v[56:57], v[34:35], 1.0 op_sel_hi:[1,0]
	v_pk_mul_f32 v[24:25], v[24:25], v[28:29]
	v_pk_mul_f32 v[28:29], v[36:37], v[40:41]
	v_pk_add_f32 v[92:93], v[32:33], 1.0 op_sel_hi:[1,0]
	v_pk_mul_f32 v[30:31], v[50:51], v[54:55]
	v_xor_b32_e32 v54, 2, v94
	v_cmp_lt_i32_e32 vcc, v54, v95
	v_pk_mul_f32 v[34:35], v[66:67], v[70:71]
	v_pk_mul_f32 v[36:37], v[64:65], v[68:69]
	v_cndmask_b32_e32 v54, v94, v54, vcc
	v_lshlrev_b32_e32 v66, 2, v54
	v_xor_b32_e32 v54, 4, v94
	v_cmp_lt_i32_e32 vcc, v54, v95
	v_pk_mul_f32 v[26:27], v[38:39], v[42:43]
	v_pk_add_f32 v[42:43], v[46:47], 1.0 op_sel_hi:[1,0]
	v_cndmask_b32_e32 v54, v94, v54, vcc
	v_lshlrev_b32_e32 v67, 2, v54
	v_xor_b32_e32 v54, 8, v94
	v_cmp_lt_i32_e32 vcc, v54, v95
	v_pk_add_f32 v[44:45], v[44:45], 1.0 op_sel_hi:[1,0]
	v_pk_mul_f32 v[32:33], v[48:49], v[52:53]
	v_cndmask_b32_e32 v54, v94, v54, vcc
	v_lshlrev_b32_e32 v68, 2, v54
	v_xor_b32_e32 v54, 16, v94
	v_cmp_lt_i32_e32 vcc, v54, v95
	v_pk_add_f32 v[46:47], v[62:63], 1.0 op_sel_hi:[1,0]
	v_pk_add_f32 v[48:49], v[60:61], 1.0 op_sel_hi:[1,0]
	v_cndmask_b32_e32 v54, v94, v54, vcc
	v_lshlrev_b32_e32 v69, 2, v54
	v_xor_b32_e32 v54, 32, v94
	v_cmp_lt_i32_e32 vcc, v54, v95
	v_pk_add_f32 v[50:51], v[74:75], 1.0 op_sel_hi:[1,0]
	v_pk_add_f32 v[52:53], v[72:73], 1.0 op_sel_hi:[1,0]
	v_cndmask_b32_e32 v54, v94, v54, vcc
	v_pk_mul_f32 v[38:39], v[78:79], v[56:57]
	v_lshlrev_b32_e32 v70, 2, v54
	v_lshl_add_u64 v[54:55], s[40:41], 0, v[16:17]
	v_lshl_add_u64 v[56:57], s[58:59], 0, v[16:17]
	v_and_b32_e32 v16, 63, v58
	v_pk_mul_f32 v[40:41], v[76:77], v[92:93]
	v_pk_mul_f32 v[42:43], v[82:83], v[42:43]
	v_pk_mul_f32 v[44:45], v[80:81], v[44:45]
	v_pk_mul_f32 v[46:47], v[86:87], v[46:47]
	v_pk_mul_f32 v[48:49], v[84:85], v[48:49]
	v_pk_mul_f32 v[50:51], v[90:91], v[50:51]
	v_pk_mul_f32 v[52:53], v[88:89], v[52:53]
	v_lshlrev_b32_e32 v16, 3, v16
	v_mov_b32_e32 v58, 0x358637bd
.LBB0_1498:
	v_lshl_add_u64 v[60:61], s[6:7], 0, v[16:17]
	v_add_co_u32_e64 v80, s[0:1], s17, v60
	v_lshl_add_u64 v[62:63], s[8:9], 0, v[16:17]
	s_nop 0
	v_addc_co_u32_e64 v81, s[0:1], 0, v61, s[0:1]
	s_add_i32 s12, s15, s14
	v_add_co_u32_e32 v64, vcc, 0x4000000, v60
	global_load_dwordx2 v[72:73], v[62:63], off nt
	global_load_dwordx2 v[74:75], v[62:63], off offset:512 nt
	global_load_dwordx2 v[76:77], v[62:63], off offset:1024 nt
	global_load_dwordx2 v[78:79], v[62:63], off offset:1536 nt
	v_add_co_u32_e64 v62, s[0:1], s18, v60
	s_ashr_i32 s13, s12, 31
	s_nop 0
	v_addc_co_u32_e64 v63, s[0:1], 0, v61, s[0:1]
	v_addc_co_u32_e32 v65, vcc, 0, v61, vcc
	s_lshl_b64 s[0:1], s[12:13], 11
	global_load_dwordx2 v[82:83], v[64:65], off offset:1536 nt
	global_load_dwordx2 v[84:85], v[64:65], off nt
	global_load_dwordx2 v[86:87], v[64:65], off offset:512 nt
	global_load_dwordx2 v[88:89], v[64:65], off offset:1024 nt
	v_lshl_add_u64 v[90:91], v[18:19], 0, s[0:1]
	v_lshl_add_u64 v[92:93], v[20:21], 0, s[0:1]
	global_load_dwordx2 v[94:95], v[90:91], off nt
	global_load_dwordx2 v[96:97], v[90:91], off offset:512 nt
	global_load_dwordx2 v[98:99], v[90:91], off offset:1024 nt
	global_load_dwordx2 v[100:101], v[90:91], off offset:1536 nt
	global_load_dwordx2 v[102:103], v[92:93], off offset:1536 nt
	global_load_dwordx2 v[104:105], v[92:93], off nt
	global_load_dwordx2 v[106:107], v[92:93], off offset:512 nt
	global_load_dwordx2 v[108:109], v[92:93], off offset:1024 nt
	v_lshl_add_u64 v[64:65], v[54:55], 0, s[0:1]
	v_lshl_add_u64 v[60:61], v[56:57], 0, s[0:1]
	s_add_i32 s14, s14, 2
	s_add_u32 s6, s6, 0x1000
	s_addc_u32 s7, s7, 0
	s_add_u32 s8, s8, 0x1000
	s_addc_u32 s9, s9, 0
	s_cmp_lt_i32 s14, s11
	s_waitcnt vmcnt(15)
	v_lshlrev_b32_e32 v90, 16, v72
	v_and_b32_e32 v91, 0xffff0000, v72
	v_lshlrev_b32_e32 v72, 16, v73
	v_and_b32_e32 v73, 0xffff0000, v73
	s_waitcnt vmcnt(14)
	v_lshlrev_b32_e32 v92, 16, v74
	v_and_b32_e32 v93, 0xffff0000, v74
	v_lshlrev_b32_e32 v74, 16, v75
	v_and_b32_e32 v75, 0xffff0000, v75
	s_waitcnt vmcnt(13)
	v_lshlrev_b32_e32 v110, 16, v76
	s_waitcnt vmcnt(11)
	v_lshlrev_b32_e32 v115, 16, v82
	s_waitcnt vmcnt(10)
	v_lshlrev_b32_e32 v118, 16, v84
	v_and_b32_e32 v119, 0xffff0000, v84
	v_lshlrev_b32_e32 v84, 16, v85
	v_and_b32_e32 v85, 0xffff0000, v85
	s_waitcnt vmcnt(9)
	v_lshlrev_b32_e32 v121, 16, v87
	v_lshlrev_b32_e32 v120, 16, v86
	v_and_b32_e32 v87, 0xffff0000, v87
	v_and_b32_e32 v86, 0xffff0000, v86
	s_waitcnt vmcnt(8)
	v_lshlrev_b32_e32 v122, 16, v88
	v_and_b32_e32 v123, 0xffff0000, v88
	v_lshlrev_b32_e32 v88, 16, v89
	v_and_b32_e32 v89, 0xffff0000, v89
	s_waitcnt vmcnt(3)
	v_lshlrev_b32_e32 v133, 16, v102
	v_mul_f32_e32 v114, v85, v85
	v_pk_mul_f32 v[136:137], v[86:87], v[86:87]
	v_mul_f32_e32 v132, v119, v119
	v_mov_b32_e32 v139, v115
	v_mul_f32_e32 v138, v89, v89
	v_mov_b32_e32 v140, v120
	v_mov_b32_e32 v141, v86
	v_mov_b32_e32 v86, v121
	s_waitcnt vmcnt(2)
	v_lshlrev_b32_e32 v142, 16, v104
	v_and_b32_e32 v143, 0xffff0000, v104
	v_lshlrev_b32_e32 v104, 16, v105
	v_and_b32_e32 v105, 0xffff0000, v105
	s_waitcnt vmcnt(1)
	v_lshlrev_b32_e32 v145, 16, v107
	v_lshlrev_b32_e32 v144, 16, v106
	v_and_b32_e32 v107, 0xffff0000, v107
	v_and_b32_e32 v106, 0xffff0000, v106
	v_pk_fma_f32 v[148:149], v[84:85], v[84:85], v[114:115] op_sel_hi:[1,1,0]
	v_pk_fma_f32 v[120:121], v[120:121], v[120:121], v[136:137]
	v_pk_fma_f32 v[136:137], v[118:119], v[118:119], v[132:133] op_sel_hi:[1,1,0]
	v_and_b32_e32 v117, 0xffff0000, v82
	v_lshlrev_b32_e32 v82, 16, v83
	v_and_b32_e32 v83, 0xffff0000, v83
	v_and_b32_e32 v135, 0xffff0000, v102
	v_mul_f32_e32 v134, v123, v123
	v_pk_fma_f32 v[152:153], v[88:89], v[88:89], v[138:139] op_sel_hi:[1,1,0]
	v_mul_f32_e32 v132, v105, v105
	v_pk_mul_f32 v[154:155], v[106:107], v[106:107]
	v_mul_f32_e32 v156, v143, v143
	v_mov_b32_e32 v157, v133
	v_mov_b32_e32 v114, v136
	v_mov_b32_e32 v138, v148
	v_mul_f32_e32 v71, v117, v117
	v_mul_f32_e32 v159, v82, v82
	v_mul_f32_e32 v161, v83, v83
	v_mov_b32_e32 v116, v115
	s_waitcnt vmcnt(0)
	v_lshlrev_b32_e32 v146, 16, v108
	v_and_b32_e32 v147, 0xffff0000, v108
	v_lshlrev_b32_e32 v108, 16, v109
	v_and_b32_e32 v109, 0xffff0000, v109
	v_pk_fma_f32 v[150:151], v[122:123], v[122:123], v[134:135] op_sel_hi:[1,1,0]
	v_mov_b32_e32 v162, v144
	v_mov_b32_e32 v163, v106
	v_mov_b32_e32 v106, v145
	v_pk_add_f32 v[136:137], v[136:137], v[148:149]
	v_pk_add_f32 v[120:121], v[120:121], v[120:121] op_sel:[0,1] op_sel_hi:[1,0]
	v_pk_fma_f32 v[148:149], v[104:105], v[104:105], v[132:133] op_sel_hi:[1,1,0]
	v_pk_fma_f32 v[144:145], v[144:145], v[144:145], v[154:155]
	v_pk_fma_f32 v[154:155], v[142:143], v[142:143], v[156:157] op_sel_hi:[1,1,0]
	v_pk_mul_f32 v[114:115], v[114:115], v[138:139]
	v_lshlrev_b32_e32 v102, 16, v103
	v_and_b32_e32 v103, 0xffff0000, v103
	v_mul_f32_e32 v158, v147, v147
	v_mul_f32_e32 v160, v109, v109
	v_mov_b32_e32 v151, v159
	v_mov_b32_e32 v153, v161
	v_mov_b32_e32 v121, v71
	v_mov_b32_e32 v132, v154
	v_mov_b32_e32 v156, v148
	v_mov_b32_e32 v137, v115
	v_mul_f32_e32 v164, v135, v135
	v_mul_f32_e32 v165, v102, v102
	v_mul_f32_e32 v166, v103, v103
	v_pk_fma_f32 v[158:159], v[146:147], v[146:147], v[158:159] op_sel_hi:[1,1,0]
	v_pk_fma_f32 v[160:161], v[108:109], v[108:109], v[160:161] op_sel_hi:[1,1,0]
	v_pk_add_f32 v[138:139], v[150:151], v[152:153]
	v_pk_add_f32 v[148:149], v[154:155], v[148:149]
	v_pk_add_f32 v[144:145], v[144:145], v[144:145] op_sel:[0,1] op_sel_hi:[1,0]
	v_pk_mul_f32 v[114:115], v[132:133], v[156:157]
	v_pk_add_f32 v[120:121], v[136:137], v[120:121]
	v_mov_b32_e32 v159, v165
	v_mov_b32_e32 v161, v166
	v_mov_b32_e32 v145, v164
	v_mov_b32_e32 v149, v115
	v_pk_add_f32 v[114:115], v[120:121], v[138:139]
	v_mov_b32_e32 v134, v133
	v_pk_add_f32 v[132:133], v[158:159], v[160:161]
	v_pk_add_f32 v[120:121], v[148:149], v[144:145]
	v_add_f32_e32 v71, v114, v115
	v_pk_add_f32 v[114:115], v[120:121], v[132:133]
	ds_bpermute_b32 v121, v59, v71
	v_mov_b32_e32 v120, v114
	v_and_b32_e32 v111, 0xffff0000, v76
	v_lshlrev_b32_e32 v76, 16, v77
	v_and_b32_e32 v77, 0xffff0000, v77
	s_waitcnt lgkmcnt(0)
	v_add_f32_e32 v71, v71, v121
	ds_bpermute_b32 v114, v66, v71
	v_lshlrev_b32_e32 v112, 16, v78
	v_and_b32_e32 v113, 0xffff0000, v78
	v_lshlrev_b32_e32 v78, 16, v79
	v_and_b32_e32 v79, 0xffff0000, v79
	s_waitcnt lgkmcnt(0)
	v_add_f32_e32 v71, v71, v114
	ds_bpermute_b32 v114, v67, v71
	v_lshlrev_b32_e32 v124, 16, v94
	v_and_b32_e32 v125, 0xffff0000, v94
	v_lshlrev_b32_e32 v94, 16, v95
	v_and_b32_e32 v95, 0xffff0000, v95
	s_waitcnt lgkmcnt(0)
	v_add_f32_e32 v71, v71, v114
	ds_bpermute_b32 v114, v68, v71
	v_lshlrev_b32_e32 v126, 16, v96
	v_and_b32_e32 v127, 0xffff0000, v96
	v_lshlrev_b32_e32 v96, 16, v97
	v_and_b32_e32 v97, 0xffff0000, v97
	s_waitcnt lgkmcnt(0)
	v_add_f32_e32 v71, v71, v114
	ds_bpermute_b32 v114, v69, v71
	v_lshlrev_b32_e32 v128, 16, v98
	v_and_b32_e32 v129, 0xffff0000, v98
	v_lshlrev_b32_e32 v98, 16, v99
	v_and_b32_e32 v99, 0xffff0000, v99
	s_waitcnt lgkmcnt(0)
	v_add_f32_e32 v71, v71, v114
	ds_bpermute_b32 v114, v70, v71
	v_lshlrev_b32_e32 v130, 16, v100
	v_and_b32_e32 v131, 0xffff0000, v100
	v_lshlrev_b32_e32 v100, 16, v101
	v_and_b32_e32 v101, 0xffff0000, v101
	s_waitcnt lgkmcnt(0)
	v_add_f32_e32 v71, v71, v114
	v_fmamk_f32 v71, v71, 0x3a800000, v58
	v_mul_f32_e32 v114, 0x4b800000, v71
	v_cmp_gt_f32_e32 vcc, s16, v71
	s_nop 1
	v_cndmask_b32_e32 v71, v71, v114, vcc
	v_rsq_f32_e32 v71, v71
	s_nop 0
	v_mul_f32_e32 v114, 0x45800000, v71
	v_cndmask_b32_e32 v114, v71, v114, vcc
	v_pk_mul_f32 v[118:119], v[114:115], v[118:119] op_sel_hi:[0,1]
	v_pk_mul_f32 v[84:85], v[114:115], v[84:85] op_sel_hi:[0,1]
	v_pk_mul_f32 v[132:133], v[114:115], v[140:141] op_sel_hi:[0,1]
	v_pk_mul_f32 v[86:87], v[114:115], v[86:87] op_sel_hi:[0,1]
	v_pk_mul_f32 v[88:89], v[114:115], v[88:89] op_sel_hi:[0,1]
	v_pk_mul_f32 v[116:117], v[114:115], v[116:117] op_sel_hi:[0,1]
	v_pk_mul_f32 v[82:83], v[114:115], v[82:83] op_sel_hi:[0,1]
	v_pk_mul_f32 v[122:123], v[114:115], v[122:123] op_sel_hi:[0,1]
	v_pk_fma_f32 v[72:73], v[22:23], v[84:85], v[72:73]
	v_pk_fma_f32 v[84:85], v[24:25], v[118:119], v[90:91]
	v_pk_fma_f32 v[74:75], v[26:27], v[86:87], v[74:75]
	v_pk_fma_f32 v[86:87], v[28:29], v[132:133], v[92:93]
	v_pk_fma_f32 v[76:77], v[30:31], v[88:89], v[76:77]
	v_pk_fma_f32 v[78:79], v[34:35], v[82:83], v[78:79]
	v_pk_fma_f32 v[82:83], v[36:37], v[116:117], v[112:113]
	v_pk_fma_f32 v[88:89], v[32:33], v[122:123], v[110:111]
	v_cvt_pk_bf16_f32 v84, v84, v85
	v_cvt_pk_bf16_f32 v85, v72, v73
	v_cvt_pk_bf16_f32 v72, v86, v87
	v_cvt_pk_bf16_f32 v73, v74, v75
	v_cvt_pk_bf16_f32 v75, v76, v77
	v_cvt_pk_bf16_f32 v76, v82, v83
	v_cvt_pk_bf16_f32 v77, v78, v79
	v_cvt_pk_bf16_f32 v74, v88, v89
	global_store_dwordx2 v[80:81], v[84:85], off
	global_store_dwordx2 v[80:81], v[72:73], off offset:512
	global_store_dwordx2 v[80:81], v[74:75], off offset:1024
	global_store_dwordx2 v[80:81], v[76:77], off offset:1536
	v_lshlrev_b32_e32 v81, 16, v85
	v_lshlrev_b32_e32 v80, 16, v84
	v_and_b32_e32 v83, 0xffff0000, v85
	v_and_b32_e32 v82, 0xffff0000, v84
	v_lshlrev_b32_e32 v85, 16, v73
	v_lshlrev_b32_e32 v84, 16, v72
	v_and_b32_e32 v73, 0xffff0000, v73
	v_and_b32_e32 v72, 0xffff0000, v72
	v_lshlrev_b32_e32 v78, 16, v74
	v_and_b32_e32 v79, 0xffff0000, v74
	v_lshlrev_b32_e32 v74, 16, v76
	v_lshlrev_b32_e32 v86, 16, v75
	v_pk_mul_f32 v[88:89], v[82:83], v[82:83]
	v_pk_mul_f32 v[90:91], v[72:73], v[72:73]
	v_and_b32_e32 v87, 0xffff0000, v75
	v_mul_f32_e32 v75, v78, v78
	v_mul_f32_e32 v93, v79, v79
	v_mul_f32_e32 v110, v86, v86
	v_mov_b32_e32 v92, v74
	v_mov_b32_e32 v116, v80
	v_mov_b32_e32 v117, v82
	v_mov_b32_e32 v82, v81
	v_mov_b32_e32 v118, v84
	v_mov_b32_e32 v119, v72
	v_mov_b32_e32 v72, v85
	v_pk_fma_f32 v[80:81], v[80:81], v[80:81], v[88:89]
	v_pk_fma_f32 v[84:85], v[84:85], v[84:85], v[90:91]
	v_and_b32_e32 v71, 0xffff0000, v76
	v_lshlrev_b32_e32 v76, 16, v77
	v_and_b32_e32 v77, 0xffff0000, v77
	v_pk_fma_f32 v[88:89], v[86:87], v[86:87], v[110:111] op_sel_hi:[1,1,0]
	v_pk_add_f32 v[90:91], v[74:75], v[92:93]
	v_pk_add_f32 v[80:81], v[80:81], v[80:81] op_sel_hi:[0,1]
	v_pk_add_f32 v[84:85], v[84:85], v[84:85] op_sel_hi:[0,1]
	v_mul_f32_e32 v112, v74, v74
	v_mul_f32_e32 v88, v71, v71
	v_mov_b32_e32 v113, v91
	v_mul_f32_e32 v80, v76, v76
	v_mul_f32_e32 v84, v77, v77
	v_pk_add_f32 v[88:89], v[112:113], v[88:89]
	v_pk_add_f32 v[80:81], v[80:81], v[84:85]
	v_mov_b32_e32 v75, v71
	v_pk_add_f32 v[80:81], v[88:89], v[80:81]
	s_nop 0
	v_mov_b32_e32 v121, v80
	v_mov_b32_e32 v80, v115
	v_pk_add_f32 v[80:81], v[120:121], v[80:81]
	ds_bpermute_b32 v85, v59, v81
	ds_bpermute_b32 v84, v59, v80
	s_waitcnt lgkmcnt(0)
	v_pk_add_f32 v[80:81], v[80:81], v[84:85]
	ds_bpermute_b32 v85, v66, v81
	ds_bpermute_b32 v84, v66, v80
	s_waitcnt lgkmcnt(0)
	v_pk_add_f32 v[80:81], v[80:81], v[84:85]
	ds_bpermute_b32 v85, v67, v81
	ds_bpermute_b32 v84, v67, v80
	s_waitcnt lgkmcnt(0)
	v_pk_add_f32 v[80:81], v[80:81], v[84:85]
	ds_bpermute_b32 v85, v68, v81
	ds_bpermute_b32 v84, v68, v80
	s_waitcnt lgkmcnt(0)
	v_pk_add_f32 v[80:81], v[80:81], v[84:85]
	ds_bpermute_b32 v85, v69, v81
	ds_bpermute_b32 v84, v69, v80
	s_waitcnt lgkmcnt(0)
	v_pk_add_f32 v[80:81], v[80:81], v[84:85]
	ds_bpermute_b32 v85, v70, v81
	ds_bpermute_b32 v84, v70, v80
	s_waitcnt lgkmcnt(0)
	v_pk_add_f32 v[80:81], v[80:81], v[84:85]
	s_nop 0
	v_pk_fma_f32 v[80:81], v[80:81], s[10:11], v[58:59] op_sel_hi:[1,0,0]
	s_nop 0
	v_mul_f32_e32 v71, 0x4b800000, v81
	v_mul_f32_e32 v84, 0x4b800000, v80
	v_cmp_gt_f32_e32 vcc, s16, v80
	v_cmp_gt_f32_e64 s[0:1], s16, v81
	s_nop 0
	v_cndmask_b32_e32 v80, v80, v84, vcc
	v_cndmask_b32_e64 v71, v81, v71, s[0:1]
	v_rsq_f32_e32 v71, v71
	v_rsq_f32_e32 v81, v80
	v_mul_f32_e32 v80, 0x45800000, v71
	v_mul_f32_e32 v84, 0x45800000, v81
	v_cndmask_b32_e64 v80, v71, v80, s[0:1]
	v_cndmask_b32_e32 v84, v81, v84, vcc
	v_pk_mul_f32 v[88:89], v[80:81], v[116:117] op_sel_hi:[0,1]
	v_pk_mul_f32 v[82:83], v[80:81], v[82:83] op_sel_hi:[0,1]
	v_pk_mul_f32 v[90:91], v[80:81], v[118:119] op_sel_hi:[0,1]
	v_pk_mul_f32 v[72:73], v[80:81], v[72:73] op_sel_hi:[0,1]
	v_pk_mul_f32 v[78:79], v[80:81], v[78:79] op_sel_hi:[0,1]
	v_pk_mul_f32 v[86:87], v[80:81], v[86:87] op_sel_hi:[0,1]
	v_pk_mul_f32 v[74:75], v[80:81], v[74:75] op_sel_hi:[0,1]
	v_pk_mul_f32 v[76:77], v[80:81], v[76:77] op_sel_hi:[0,1]
	v_pk_mul_f32 v[80:81], v[84:85], v[142:143] op_sel_hi:[0,1]
	v_pk_mul_f32 v[92:93], v[84:85], v[104:105] op_sel_hi:[0,1]
	v_pk_mul_f32 v[104:105], v[84:85], v[162:163] op_sel_hi:[0,1]
	v_pk_mul_f32 v[106:107], v[84:85], v[106:107] op_sel_hi:[0,1]
	v_pk_mul_f32 v[110:111], v[84:85], v[146:147] op_sel_hi:[0,1]
	v_pk_mul_f32 v[108:109], v[84:85], v[108:109] op_sel_hi:[0,1]
	v_pk_mul_f32 v[112:113], v[84:85], v[134:135] op_sel_hi:[0,1]
	v_pk_mul_f32 v[84:85], v[84:85], v[102:103] op_sel_hi:[0,1]
	v_pk_fma_f32 v[82:83], v[38:39], v[82:83], v[2:3]
	v_pk_fma_f32 v[88:89], v[40:41], v[88:89], v[0:1]
	v_pk_fma_f32 v[72:73], v[42:43], v[72:73], v[6:7]
	v_pk_fma_f32 v[90:91], v[44:45], v[90:91], v[4:5]
	v_pk_fma_f32 v[78:79], v[48:49], v[78:79], v[8:9]
	v_pk_fma_f32 v[76:77], v[50:51], v[76:77], v[14:15]
	v_pk_fma_f32 v[74:75], v[52:53], v[74:75], v[12:13]
	v_pk_fma_f32 v[92:93], v[22:23], v[92:93], v[94:95]
	v_pk_fma_f32 v[80:81], v[24:25], v[80:81], v[124:125]
	v_pk_fma_f32 v[94:95], v[26:27], v[106:107], v[96:97]
	v_pk_fma_f32 v[96:97], v[28:29], v[104:105], v[126:127]
	v_pk_fma_f32 v[86:87], v[46:47], v[86:87], v[10:11]
	v_pk_fma_f32 v[98:99], v[30:31], v[108:109], v[98:99]
	v_pk_fma_f32 v[102:103], v[32:33], v[110:111], v[128:129]
	v_pk_fma_f32 v[84:85], v[34:35], v[84:85], v[100:101]
	v_pk_fma_f32 v[100:101], v[36:37], v[112:113], v[130:131]
	v_cvt_pk_bf16_f32 v88, v88, v89
	v_cvt_pk_bf16_f32 v89, v82, v83
	v_cvt_pk_bf16_f32 v82, v90, v91
	v_cvt_pk_bf16_f32 v83, v72, v73
	v_cvt_pk_bf16_f32 v72, v78, v79
	v_cvt_pk_bf16_f32 v74, v74, v75
	v_cvt_pk_bf16_f32 v75, v76, v77
	v_cvt_pk_bf16_f32 v76, v80, v81
	v_cvt_pk_bf16_f32 v77, v92, v93
	v_cvt_pk_bf16_f32 v78, v96, v97
	v_cvt_pk_bf16_f32 v79, v94, v95
	v_cvt_pk_bf16_f32 v73, v86, v87
	v_cvt_pk_bf16_f32 v80, v102, v103
	v_cvt_pk_bf16_f32 v81, v98, v99
	v_cvt_pk_bf16_f32 v86, v100, v101
	v_cvt_pk_bf16_f32 v87, v84, v85
	global_store_dwordx2 v[62:63], v[88:89], off
	global_store_dwordx2 v[62:63], v[82:83], off offset:512
	global_store_dwordx2 v[62:63], v[72:73], off offset:1024
	global_store_dwordx2 v[62:63], v[74:75], off offset:1536
	global_store_dwordx2 v[64:65], v[76:77], off
	global_store_dwordx2 v[64:65], v[78:79], off offset:512
	global_store_dwordx2 v[64:65], v[80:81], off offset:1024
	v_lshlrev_b32_e32 v75, 16, v77
	v_lshlrev_b32_e32 v74, 16, v76
	v_and_b32_e32 v77, 0xffff0000, v77
	v_and_b32_e32 v76, 0xffff0000, v76
	v_lshlrev_b32_e32 v83, 16, v79
	v_lshlrev_b32_e32 v82, 16, v78
	v_and_b32_e32 v79, 0xffff0000, v79
	v_and_b32_e32 v78, 0xffff0000, v78
	v_lshlrev_b32_e32 v62, 16, v80
	v_and_b32_e32 v63, 0xffff0000, v80
	global_store_dwordx2 v[64:65], v[86:87], off offset:1536
	v_lshlrev_b32_e32 v64, 16, v86
	v_and_b32_e32 v71, 0xffff0000, v86
	v_lshlrev_b32_e32 v72, 16, v87
	v_and_b32_e32 v73, 0xffff0000, v87
	v_lshlrev_b32_e32 v80, 16, v81
	v_pk_mul_f32 v[84:85], v[76:77], v[76:77]
	v_pk_mul_f32 v[86:87], v[78:79], v[78:79]
	v_and_b32_e32 v81, 0xffff0000, v81
	v_mul_f32_e32 v65, v62, v62
	v_mul_f32_e32 v89, v63, v63
	v_mul_f32_e32 v90, v80, v80
	v_mov_b32_e32 v88, v64
	v_mov_b32_e32 v94, v74
	v_mov_b32_e32 v95, v76
	v_mov_b32_e32 v76, v75
	v_mov_b32_e32 v96, v82
	v_mov_b32_e32 v97, v78
	v_mov_b32_e32 v78, v83
	v_pk_fma_f32 v[74:75], v[74:75], v[74:75], v[84:85]
	v_pk_fma_f32 v[82:83], v[82:83], v[82:83], v[86:87]
	v_pk_fma_f32 v[84:85], v[80:81], v[80:81], v[90:91] op_sel_hi:[1,1,0]
	v_pk_add_f32 v[86:87], v[64:65], v[88:89]
	v_pk_add_f32 v[74:75], v[74:75], v[74:75] op_sel_hi:[0,1]
	v_pk_add_f32 v[82:83], v[82:83], v[82:83] op_sel_hi:[0,1]
	v_mul_f32_e32 v92, v64, v64
	v_mul_f32_e32 v84, v71, v71
	v_mov_b32_e32 v93, v87
	v_mul_f32_e32 v74, v72, v72
	v_mul_f32_e32 v82, v73, v73
	v_pk_add_f32 v[84:85], v[92:93], v[84:85]
	v_pk_add_f32 v[74:75], v[74:75], v[82:83]
	v_mov_b32_e32 v65, v71
	v_pk_add_f32 v[74:75], v[84:85], v[74:75]
	s_nop 0
	v_add_f32_e32 v71, v74, v75
	ds_bpermute_b32 v74, v59, v71
	s_waitcnt lgkmcnt(0)
	v_add_f32_e32 v71, v71, v74
	ds_bpermute_b32 v74, v66, v71
	s_waitcnt lgkmcnt(0)
	v_add_f32_e32 v71, v71, v74
	ds_bpermute_b32 v74, v67, v71
	s_waitcnt lgkmcnt(0)
	v_add_f32_e32 v71, v71, v74
	ds_bpermute_b32 v74, v68, v71
	s_waitcnt lgkmcnt(0)
	v_add_f32_e32 v71, v71, v74
	ds_bpermute_b32 v74, v69, v71
	s_waitcnt lgkmcnt(0)
	v_add_f32_e32 v71, v71, v74
	ds_bpermute_b32 v74, v70, v71
	s_waitcnt lgkmcnt(0)
	v_add_f32_e32 v71, v71, v74
	v_fmamk_f32 v71, v71, 0x3a800000, v58
	v_mul_f32_e32 v74, 0x4b800000, v71
	v_cmp_gt_f32_e32 vcc, s16, v71
	s_nop 1
	v_cndmask_b32_e32 v71, v71, v74, vcc
	v_rsq_f32_e32 v71, v71
	s_nop 0
	v_mul_f32_e32 v74, 0x45800000, v71
	v_cndmask_b32_e32 v74, v71, v74, vcc
	v_pk_mul_f32 v[82:83], v[74:75], v[94:95] op_sel_hi:[0,1]
	v_pk_mul_f32 v[76:77], v[74:75], v[76:77] op_sel_hi:[0,1]
	v_pk_mul_f32 v[84:85], v[74:75], v[96:97] op_sel_hi:[0,1]
	v_pk_mul_f32 v[78:79], v[74:75], v[78:79] op_sel_hi:[0,1]
	v_pk_mul_f32 v[62:63], v[74:75], v[62:63] op_sel_hi:[0,1]
	v_pk_mul_f32 v[80:81], v[74:75], v[80:81] op_sel_hi:[0,1]
	v_pk_mul_f32 v[64:65], v[74:75], v[64:65] op_sel_hi:[0,1]
	v_pk_mul_f32 v[72:73], v[74:75], v[72:73] op_sel_hi:[0,1]
	v_pk_fma_f32 v[74:75], v[38:39], v[76:77], v[2:3]
	v_pk_fma_f32 v[76:77], v[40:41], v[82:83], v[0:1]
	v_pk_fma_f32 v[78:79], v[42:43], v[78:79], v[6:7]
	v_pk_fma_f32 v[82:83], v[44:45], v[84:85], v[4:5]
	v_pk_fma_f32 v[80:81], v[46:47], v[80:81], v[10:11]
	v_pk_fma_f32 v[62:63], v[48:49], v[62:63], v[8:9]
	v_pk_fma_f32 v[72:73], v[50:51], v[72:73], v[14:15]
	v_pk_fma_f32 v[64:65], v[52:53], v[64:65], v[12:13]
	v_cvt_pk_bf16_f32 v76, v76, v77
	v_cvt_pk_bf16_f32 v77, v74, v75
	v_cvt_pk_bf16_f32 v74, v82, v83
	v_cvt_pk_bf16_f32 v75, v78, v79
	v_cvt_pk_bf16_f32 v62, v62, v63
	v_cvt_pk_bf16_f32 v63, v80, v81
	v_cvt_pk_bf16_f32 v64, v64, v65
	v_cvt_pk_bf16_f32 v65, v72, v73
	global_store_dwordx2 v[60:61], v[76:77], off
	global_store_dwordx2 v[60:61], v[74:75], off offset:512
	global_store_dwordx2 v[60:61], v[62:63], off offset:1024
	global_store_dwordx2 v[60:61], v[64:65], off offset:1536
	s_cbranch_scc1 .LBB0_1498

.LBB0_1711:
	s_cmp_lt_i32 s48, 20
	s_cselect_b64 s[4:5], -1, 0
	s_and_b64 s[0:1], s[4:5], s[0:1]
	s_andn2_b64 vcc, exec, s[0:1]
	s_cbranch_vccnz .LBB0_1715
	s_lshl_b32 s0, s3, 3
	s_abs_i32 s1, s0
	v_cvt_f32_u32_e32 v0, s1
	s_sub_i32 s3, 0, s1
	s_ashr_i32 s0, s0, 31
	s_mov_b32 s8, 0
	v_rcp_iflag_f32_e32 v0, v0
	s_nop 0
	v_mul_f32_e32 v0, 0x4f7ffffe, v0
	v_cvt_u32_f32_e32 v0, v0
	s_nop 0
	v_readfirstlane_b32 s4, v0
	s_mul_i32 s3, s3, s4
	s_mul_hi_u32 s3, s4, s3
	s_add_i32 s4, s4, s3
	s_lshr_b32 s3, s4, 17
	s_mul_i32 s4, s3, s1
	s_sub_i32 s4, 0x8000, s4
	s_add_i32 s5, s3, 1
	s_sub_i32 s6, s4, s1
	s_cmp_ge_u32 s4, s1
	s_cselect_b32 s3, s5, s3
	s_cselect_b32 s4, s6, s4
	s_add_i32 s5, s3, 1
	s_cmp_ge_u32 s4, s1
	s_cselect_b32 s1, s5, s3
	s_xor_b32 s1, s1, s0
	s_sub_i32 s3, s1, s0
	s_cmp_lt_i32 s3, 1
	s_cbranch_scc1 .LBB0_1715
	v_readlane_b32 s0, v247, 3
	v_readlane_b32 s1, v247, 4
	s_add_u32 s4, s0, 0x7000
	s_addc_u32 s5, s1, 0
	s_lshl_b32 s0, s2, 3
	v_readlane_b32 s1, v247, 2
	s_add_i32 s0, s1, s0
	s_mul_i32 s0, s3, s0
	s_ashr_i32 s1, s0, 31
	s_lshr_b32 s2, s1, 19
	s_add_i32 s2, s0, s2
	s_ashr_i32 s2, s2, 13
	s_mul_i32 s6, s2, 0x1800
	s_ashr_i32 s7, s6, 31
	v_lshlrev_b32_e32 v0, 2, v190
	s_lshl_b64 s[6:7], s[6:7], 2
	v_and_b32_e32 v4, 0xfc, v0
	s_add_u32 s6, s46, s6
	s_addc_u32 s7, s47, s7
	v_lshlrev_b32_e32 v8, 2, v4
	v_mov_b32_e32 v9, 0
	v_lshl_add_u64 v[0:1], s[6:7], 0, v[8:9]
	s_mov_b64 s[6:7], 0x11d000
	s_mov_b32 s2, 0x11d000
	v_lshl_add_u64 v[2:3], v[0:1], 0, s[6:7]
	v_add_co_u32_e32 v0, vcc, s2, v0
	s_add_i32 s9, s0, 1
	s_nop 0
	v_addc_co_u32_e32 v1, vcc, 0, v1, vcc
	global_load_dwordx4 v[10:13], v[0:1], off nt
	global_load_dwordx4 v[14:17], v8, s[4:5]
	v_or_b32_e32 v0, 0x400, v8
	global_load_dwordx4 v[18:21], v[2:3], off offset:1024 nt
	global_load_dwordx4 v[22:25], v[2:3], off offset:2048 nt
	v_or_b32_e32 v1, 0x800, v8
	global_load_dwordx4 v[28:31], v0, s[4:5]
	global_load_dwordx4 v[32:35], v1, s[4:5]
	v_or_b32_e32 v0, 0xc00, v8
	global_load_dwordx4 v[44:47], v0, s[4:5]
	global_load_dwordx4 v[48:51], v[2:3], off offset:3072 nt
	v_mbcnt_lo_u32_b32 v0, -1, 0
	v_mbcnt_hi_u32_b32 v6, -1, v0
	v_lshlrev_b32_e32 v2, 1, v4
	v_and_b32_e32 v4, 64, v6
	v_xor_b32_e32 v7, 1, v6
	v_add_u32_e32 v40, 64, v4
	v_xor_b32_e32 v27, 2, v6
	v_cmp_lt_i32_e32 vcc, v7, v40
	v_xor_b32_e32 v36, 4, v6
	v_xor_b32_e32 v37, 8, v6
	v_cndmask_b32_e32 v7, v6, v7, vcc
	v_cmp_lt_i32_e32 vcc, v27, v40
	s_waitcnt lgkmcnt(0)
	v_lshl_add_u64 v[4:5], s[38:39], 0, v[8:9]
	v_xor_b32_e32 v38, 16, v6
	v_cndmask_b32_e32 v8, v6, v27, vcc
	v_cmp_lt_i32_e32 vcc, v36, v40
	s_lshl_b64 s[10:11], s[0:1], 11
	v_xor_b32_e32 v39, 32, v6
	v_cndmask_b32_e32 v36, v6, v36, vcc
	v_cmp_lt_i32_e32 vcc, v37, v40
	s_add_u32 s10, s46, s10
	v_and_b32_e32 v26, 63, v190
	v_cndmask_b32_e32 v37, v6, v37, vcc
	v_cmp_lt_i32_e32 vcc, v38, v40
	s_addc_u32 s11, s47, s11
	s_lshl_b64 s[0:1], s[0:1], 12
	v_cndmask_b32_e32 v41, v6, v38, vcc
	v_cmp_lt_i32_e32 vcc, v39, v40
	v_lshlrev_b32_e32 v38, 2, v8
	v_lshlrev_b32_e32 v8, 3, v26
	v_cndmask_b32_e32 v6, v6, v39, vcc
	s_add_u32 s0, s38, s0
	v_lshlrev_b32_e32 v27, 2, v7
	v_lshlrev_b32_e32 v42, 2, v6
	v_lshl_add_u64 v[6:7], s[10:11], 0, v[8:9]
	v_lshlrev_b32_e32 v8, 4, v26
	s_addc_u32 s1, s39, s1
	s_mov_b64 s[4:5], 0xc000000
	s_mov_b64 s[6:7], 0xc00
	v_mov_b32_e32 v3, v9
	v_lshlrev_b32_e32 v39, 2, v36
	v_lshlrev_b32_e32 v40, 2, v37
	v_lshl_add_u64 v[36:37], s[0:1], 0, v[8:9]
	v_lshl_add_u64 v[0:1], s[40:41], 0, v[2:3]
	v_lshl_add_u64 v[2:3], s[36:37], 0, v[2:3]
	v_lshlrev_b32_e32 v41, 2, v41
	v_lshl_add_u64 v[6:7], v[6:7], 0, s[4:5]
	s_mov_b32 s2, 0x3a800000
	s_mov_b32 s10, 0x800000
	s_mov_b64 s[4:5], 0x1000
	v_mov_b32_e32 v26, 0x358637bd
	s_waitcnt vmcnt(0)
	v_pk_mul_f32 v[8:9], v[12:13], v[16:17]
	v_pk_mul_f32 v[10:11], v[10:11], v[14:15]
	v_pk_mul_f32 v[12:13], v[20:21], v[30:31]
	v_pk_mul_f32 v[14:15], v[18:19], v[28:29]
	v_pk_mul_f32 v[16:17], v[24:25], v[34:35]
	v_pk_mul_f32 v[18:19], v[22:23], v[32:33]
	v_pk_mul_f32 v[20:21], v[50:51], v[46:47]
	v_pk_mul_f32 v[22:23], v[48:49], v[44:45]
	v_lshl_add_u64 v[24:25], v[36:37], 0, s[6:7]
	s_mov_b64 s[6:7], 0x2000
.LBB0_1714:
	v_add_co_u32_e32 v36, vcc, 0xf8000000, v6
	s_add_i32 s0, s9, s8
	s_nop 0
	v_addc_co_u32_e32 v37, vcc, -1, v7, vcc
	v_add_co_u32_e32 v44, vcc, 0xf8001000, v6
	global_load_dwordx2 v[28:29], v[6:7], off nt
	global_load_dwordx2 v[30:31], v[6:7], off offset:512 nt
	global_load_dwordx2 v[32:33], v[6:7], off offset:1024 nt
	global_load_dwordx2 v[34:35], v[6:7], off offset:1536 nt
	s_ashr_i32 s1, s0, 31
	global_load_dwordx2 v[36:37], v[36:37], off nt
	v_addc_co_u32_e32 v45, vcc, -1, v7, vcc
	s_lshl_b64 s[12:13], s[0:1], 11
	global_load_dwordx2 v[46:47], v[44:45], off offset:-2560 nt
	global_load_dwordx2 v[48:49], v[44:45], off offset:-3584 nt
	global_load_dwordx2 v[50:51], v[44:45], off offset:-3072 nt
	v_lshl_add_u64 v[44:45], v[0:1], 0, s[12:13]
	v_lshl_add_u64 v[52:53], v[2:3], 0, s[12:13]
	global_load_dwordx2 v[54:55], v[44:45], off nt
	global_load_dwordx2 v[56:57], v[44:45], off offset:512 nt
	global_load_dwordx2 v[58:59], v[44:45], off offset:1024 nt
	global_load_dwordx2 v[60:61], v[44:45], off offset:1536 nt
	global_load_dwordx2 v[62:63], v[52:53], off offset:1536 nt
	global_load_dwordx2 v[64:65], v[52:53], off nt
	global_load_dwordx2 v[66:67], v[52:53], off offset:512 nt
	global_load_dwordx2 v[70:71], v[52:53], off offset:1024 nt
	s_lshl_b64 s[0:1], s[0:1], 12
	v_lshl_add_u64 v[68:69], v[4:5], 0, s[0:1]
	s_add_i32 s8, s8, 2
	v_lshl_add_u64 v[6:7], v[6:7], 0, s[4:5]
	s_cmp_lt_i32 s8, s3
	s_waitcnt vmcnt(14)
	v_lshlrev_b32_e32 v72, 16, v31
	v_and_b32_e32 v73, 0xffff0000, v31
	s_waitcnt vmcnt(13)
	v_lshlrev_b32_e32 v76, 16, v33
	v_and_b32_e32 v77, 0xffff0000, v33
	s_waitcnt vmcnt(11)
	v_and_b32_e32 v31, 0xffff0000, v36
	v_and_b32_e32 v33, 0xffff0000, v37
	v_lshlrev_b32_e32 v52, 16, v30
	v_and_b32_e32 v53, 0xffff0000, v30
	v_lshlrev_b32_e32 v74, 16, v32
	v_and_b32_e32 v75, 0xffff0000, v32
	v_lshlrev_b32_e32 v78, 16, v34
	v_and_b32_e32 v79, 0xffff0000, v34
	v_lshlrev_b32_e32 v80, 16, v35
	v_and_b32_e32 v81, 0xffff0000, v35
	v_lshlrev_b32_e32 v30, 16, v36
	v_lshlrev_b32_e32 v32, 16, v37
	s_waitcnt vmcnt(10)
	v_lshlrev_b32_e32 v35, 16, v46
	v_and_b32_e32 v37, 0xffff0000, v46
	v_mul_f32_e32 v34, v33, v33
	s_waitcnt vmcnt(9)
	v_lshlrev_b32_e32 v83, 16, v49
	v_lshlrev_b32_e32 v82, 16, v48
	v_and_b32_e32 v49, 0xffff0000, v49
	v_and_b32_e32 v48, 0xffff0000, v48
	s_waitcnt vmcnt(8)
	v_and_b32_e32 v85, 0xffff0000, v50
	v_mul_f32_e32 v36, v31, v31
	v_lshlrev_b32_e32 v84, 16, v50
	v_lshlrev_b32_e32 v50, 16, v51
	v_and_b32_e32 v51, 0xffff0000, v51
	s_waitcnt vmcnt(5)
	v_lshlrev_b32_e32 v90, 16, v58
	v_and_b32_e32 v91, 0xffff0000, v58
	v_lshlrev_b32_e32 v92, 16, v59
	v_and_b32_e32 v93, 0xffff0000, v59
	s_waitcnt vmcnt(3)
	v_lshlrev_b32_e32 v59, 16, v62
	v_pk_fma_f32 v[98:99], v[32:33], v[32:33], v[34:35] op_sel_hi:[1,1,0]
	v_pk_mul_f32 v[100:101], v[48:49], v[48:49]
	v_pk_fma_f32 v[102:103], v[30:31], v[30:31], v[36:37] op_sel_hi:[1,1,0]
	v_mul_f32_e32 v58, v85, v85
	s_waitcnt vmcnt(2)
	v_lshlrev_b32_e32 v106, 16, v64
	v_and_b32_e32 v107, 0xffff0000, v64
	v_lshlrev_b32_e32 v64, 16, v65
	v_and_b32_e32 v65, 0xffff0000, v65
	s_waitcnt vmcnt(1)
	v_lshlrev_b32_e32 v109, 16, v67
	v_lshlrev_b32_e32 v108, 16, v66
	v_and_b32_e32 v67, 0xffff0000, v67
	v_and_b32_e32 v66, 0xffff0000, v66
	v_lshlrev_b32_e32 v46, 16, v47
	v_and_b32_e32 v47, 0xffff0000, v47
	v_lshlrev_b32_e32 v94, 16, v60
	v_and_b32_e32 v95, 0xffff0000, v60
	v_lshlrev_b32_e32 v96, 16, v61
	v_and_b32_e32 v97, 0xffff0000, v61
	v_and_b32_e32 v61, 0xffff0000, v62
	v_mov_b32_e32 v105, v35
	v_mul_f32_e32 v60, v51, v51
	v_mov_b32_e32 v112, v82
	v_mov_b32_e32 v113, v48
	v_mov_b32_e32 v48, v83
	v_pk_fma_f32 v[82:83], v[82:83], v[82:83], v[100:101]
	v_mov_b32_e32 v34, v102
	v_mov_b32_e32 v104, v98
	v_pk_fma_f32 v[100:101], v[84:85], v[84:85], v[58:59] op_sel_hi:[1,1,0]
	v_mul_f32_e32 v58, v65, v65
	v_pk_mul_f32 v[114:115], v[66:67], v[66:67]
	v_mul_f32_e32 v116, v107, v107
	v_mov_b32_e32 v117, v59
	v_mul_f32_e32 v119, v46, v46
	v_mul_f32_e32 v121, v47, v47
	s_waitcnt vmcnt(0)
	v_lshlrev_b32_e32 v110, 16, v70
	v_and_b32_e32 v111, 0xffff0000, v70
	v_lshlrev_b32_e32 v70, 16, v71
	v_and_b32_e32 v71, 0xffff0000, v71
	v_mov_b32_e32 v36, v35
	v_pk_add_f32 v[98:99], v[102:103], v[98:99]
	v_pk_fma_f32 v[102:103], v[50:51], v[50:51], v[60:61] op_sel_hi:[1,1,0]
	v_mov_b32_e32 v122, v108
	v_mov_b32_e32 v123, v66
	v_mov_b32_e32 v66, v109
	v_pk_mul_f32 v[34:35], v[34:35], v[104:105]
	v_pk_fma_f32 v[104:105], v[64:65], v[64:65], v[58:59] op_sel_hi:[1,1,0]
	v_pk_fma_f32 v[108:109], v[108:109], v[108:109], v[114:115]
	v_pk_fma_f32 v[114:115], v[106:107], v[106:107], v[116:117] op_sel_hi:[1,1,0]
	v_lshlrev_b32_e32 v62, 16, v63
	v_and_b32_e32 v63, 0xffff0000, v63
	v_mul_f32_e32 v118, v111, v111
	v_mul_f32_e32 v120, v71, v71
	v_mov_b32_e32 v101, v119
	v_mov_b32_e32 v103, v121
	v_mov_b32_e32 v58, v114
	v_mov_b32_e32 v116, v104
	v_mul_f32_e32 v43, v37, v37
	v_mul_f32_e32 v124, v61, v61
	v_mul_f32_e32 v125, v62, v62
	v_mul_f32_e32 v126, v63, v63
	v_mov_b32_e32 v60, v59
	v_pk_add_f32 v[82:83], v[82:83], v[82:83] op_sel:[0,1] op_sel_hi:[1,0]
	v_pk_fma_f32 v[118:119], v[110:111], v[110:111], v[118:119] op_sel_hi:[1,1,0]
	v_pk_fma_f32 v[120:121], v[70:71], v[70:71], v[120:121] op_sel_hi:[1,1,0]
	v_mov_b32_e32 v99, v35
	v_pk_add_f32 v[34:35], v[100:101], v[102:103]
	v_pk_add_f32 v[100:101], v[114:115], v[104:105]
	v_pk_add_f32 v[102:103], v[108:109], v[108:109] op_sel:[0,1] op_sel_hi:[1,0]
	v_pk_mul_f32 v[58:59], v[58:59], v[116:117]
	v_mov_b32_e32 v83, v43
	v_mov_b32_e32 v119, v125
	v_mov_b32_e32 v121, v126
	v_mov_b32_e32 v103, v124
	v_mov_b32_e32 v101, v59
	v_pk_add_f32 v[82:83], v[98:99], v[82:83]
	v_pk_add_f32 v[98:99], v[118:119], v[120:121]
	v_pk_add_f32 v[58:59], v[100:101], v[102:103]
	v_pk_add_f32 v[34:35], v[82:83], v[34:35]
	v_pk_add_f32 v[58:59], v[58:59], v[98:99]
	v_mov_b32_e32 v83, v34
	v_mov_b32_e32 v82, v58
	v_mov_b32_e32 v34, v59
	v_pk_add_f32 v[34:35], v[82:83], v[34:35]
	ds_bpermute_b32 v59, v27, v35
	ds_bpermute_b32 v58, v27, v34
	v_lshlrev_b32_e32 v44, 16, v28
	v_and_b32_e32 v45, 0xffff0000, v28
	v_lshlrev_b32_e32 v28, 16, v29
	v_and_b32_e32 v29, 0xffff0000, v29
	s_waitcnt lgkmcnt(0)
	v_pk_add_f32 v[34:35], v[34:35], v[58:59]
	ds_bpermute_b32 v59, v38, v35
	ds_bpermute_b32 v58, v38, v34
	v_lshlrev_b32_e32 v86, 16, v54
	v_and_b32_e32 v87, 0xffff0000, v54
	v_lshlrev_b32_e32 v54, 16, v55
	v_and_b32_e32 v55, 0xffff0000, v55
	s_waitcnt lgkmcnt(0)
	v_pk_add_f32 v[34:35], v[34:35], v[58:59]
	ds_bpermute_b32 v59, v39, v35
	ds_bpermute_b32 v58, v39, v34
	v_lshlrev_b32_e32 v88, 16, v56
	v_and_b32_e32 v89, 0xffff0000, v56
	v_lshlrev_b32_e32 v56, 16, v57
	v_and_b32_e32 v57, 0xffff0000, v57
	s_waitcnt lgkmcnt(0)
	v_pk_add_f32 v[34:35], v[34:35], v[58:59]
	ds_bpermute_b32 v59, v40, v35
	ds_bpermute_b32 v58, v40, v34
	s_waitcnt lgkmcnt(0)
	v_pk_add_f32 v[34:35], v[34:35], v[58:59]
	ds_bpermute_b32 v59, v41, v35
	ds_bpermute_b32 v58, v41, v34
	s_waitcnt lgkmcnt(0)
	v_pk_add_f32 v[34:35], v[34:35], v[58:59]
	ds_bpermute_b32 v59, v42, v35
	ds_bpermute_b32 v58, v42, v34
	s_waitcnt lgkmcnt(0)
	v_pk_add_f32 v[34:35], v[34:35], v[58:59]
	s_nop 0
	v_pk_fma_f32 v[34:35], v[34:35], s[2:3], v[26:27] op_sel_hi:[1,0,0]
	s_nop 0
	v_mul_f32_e32 v43, 0x4b800000, v35
	v_cmp_gt_f32_e64 s[0:1], s10, v35
	v_mul_f32_e32 v58, 0x4b800000, v34
	v_cmp_gt_f32_e32 vcc, s10, v34
	v_cndmask_b32_e64 v35, v35, v43, s[0:1]
	v_rsq_f32_e32 v35, v35
	v_cndmask_b32_e32 v34, v34, v58, vcc
	v_rsq_f32_e32 v43, v34
	v_mul_f32_e32 v34, 0x45800000, v35
	v_cndmask_b32_e64 v34, v35, v34, s[0:1]
	v_mul_f32_e32 v58, 0x45800000, v43
	v_cndmask_b32_e32 v58, v43, v58, vcc
	v_pk_mul_f32 v[82:83], v[34:35], v[30:31] op_sel_hi:[0,1]
	v_pk_mul_f32 v[30:31], v[34:35], v[32:33] op_sel_hi:[0,1]
	v_pk_mul_f32 v[32:33], v[34:35], v[112:113] op_sel_hi:[0,1]
	v_pk_mul_f32 v[48:49], v[34:35], v[48:49] op_sel_hi:[0,1]
	v_pk_mul_f32 v[84:85], v[34:35], v[84:85] op_sel_hi:[0,1]
	v_pk_mul_f32 v[50:51], v[34:35], v[50:51] op_sel_hi:[0,1]
	v_pk_mul_f32 v[36:37], v[34:35], v[36:37] op_sel_hi:[0,1]
	v_pk_mul_f32 v[98:99], v[34:35], v[46:47] op_sel_hi:[0,1]
	v_pk_mul_f32 v[100:101], v[58:59], v[106:107] op_sel_hi:[0,1]
	v_pk_mul_f32 v[64:65], v[58:59], v[64:65] op_sel_hi:[0,1]
	v_pk_mul_f32 v[102:103], v[58:59], v[122:123] op_sel_hi:[0,1]
	v_pk_mul_f32 v[66:67], v[58:59], v[66:67] op_sel_hi:[0,1]
	v_pk_mul_f32 v[104:105], v[58:59], v[110:111] op_sel_hi:[0,1]
	v_pk_mul_f32 v[70:71], v[58:59], v[70:71] op_sel_hi:[0,1]
	v_pk_mul_f32 v[106:107], v[58:59], v[60:61] op_sel_hi:[0,1]
	v_pk_mul_f32 v[108:109], v[58:59], v[62:63] op_sel_hi:[0,1]
	v_pk_fma_f32 v[30:31], v[8:9], v[30:31], v[28:29]
	v_pk_fma_f32 v[28:29], v[10:11], v[82:83], v[44:45]
	v_pk_fma_f32 v[34:35], v[12:13], v[48:49], v[72:73]
	v_pk_fma_f32 v[32:33], v[14:15], v[32:33], v[52:53]
	v_pk_fma_f32 v[46:47], v[16:17], v[50:51], v[76:77]
	v_pk_fma_f32 v[44:45], v[18:19], v[84:85], v[74:75]
	v_pk_fma_f32 v[50:51], v[20:21], v[98:99], v[80:81]
	v_pk_fma_f32 v[48:49], v[22:23], v[36:37], v[78:79]
	v_pk_fma_f32 v[54:55], v[8:9], v[64:65], v[54:55]
	v_pk_fma_f32 v[52:53], v[10:11], v[100:101], v[86:87]
	v_pk_fma_f32 v[58:59], v[12:13], v[66:67], v[56:57]
	v_pk_fma_f32 v[56:57], v[14:15], v[102:103], v[88:89]
	v_pk_fma_f32 v[62:63], v[16:17], v[70:71], v[92:93]
	v_pk_fma_f32 v[60:61], v[18:19], v[104:105], v[90:91]
	v_pk_fma_f32 v[66:67], v[20:21], v[108:109], v[96:97]
	v_pk_fma_f32 v[64:65], v[22:23], v[106:107], v[94:95]
	global_store_dwordx4 v[24:25], v[28:31], off offset:-3072
	global_store_dwordx4 v[24:25], v[32:35], off offset:-2048
	global_store_dwordx4 v[24:25], v[44:47], off offset:-1024
	global_store_dwordx4 v[24:25], v[48:51], off
	global_store_dwordx4 v[68:69], v[52:55], off
	global_store_dwordx4 v[68:69], v[56:59], off offset:1024
	global_store_dwordx4 v[68:69], v[60:63], off offset:2048
	global_store_dwordx4 v[68:69], v[64:67], off offset:3072
	v_lshl_add_u64 v[24:25], v[24:25], 0, s[6:7]
	s_cbranch_scc1 .LBB0_1714
